# speedup vs baseline: 1.0039x; 1.0029x over previous
; __device__ __forceinline__ int ltid() { int t = threadIdx.x; asm volatile("" : "+v"(t)); return t; }
; template <int AI>
; __device__ __forceinline__ void dump_half(const f32x4 (&acc)[2][2][4][2], float* stage) {
;   const int wid = ltid() >> 6, lane = ltid() & 63, wr = wid >> 2, wc = wid & 3, fr = lane & 15, fq = lane >> 4;
; #pragma unroll
;   for (int bj = 0; bj < 2; ++bj)
; #pragma unroll
;     for (int m = 0; m < 4; ++m)
; #pragma unroll
;       for (int n = 0; n < 2; ++n) {
;         const int r0 = wr * 64 + m * 16 + fq * 4, c = bj * 128 + wc * 32 + n * 16 + fr;
; #pragma unroll
;         for (int j = 0; j < 4; ++j) stage[(r0 + j) * SP + c] = acc[AI][bj][m][n][j];
;       }
; }
; __device__ __forceinline__ void emit_rm(const float* stage, u16* dst, long ld, const float* rs) {
;   const int tid = ltid(), c4 = (tid & 31) * 4, rr = tid >> 5;
; #pragma unroll 1
;   for (int ps = 0; ps < 8; ++ps) {
;     const int r = ps * 16 + rr;
;     const float* s = stage + r * SP + c4;
;     const float4 a = *(const float4*)s, b = *(const float4*)(s + 128);
;     const float f = rs ? rs[r] : 1.f;
;     uint2 o0, o1;
;     o0.x = pack2(a.x * f, a.y * f); o0.y = pack2(a.z * f, a.w * f);
;     o1.x = pack2(b.x * f, b.y * f); o1.y = pack2(b.z * f, b.w * f);
;     *(uint2*)(dst + (long)r * ld + c4) = o0;
;     *(uint2*)(dst + (long)r * ld + 128 + c4) = o1;
;   }
; }
; template <int KIND>
; __device__ __forceinline__ void tile_emit(const Ctx& p, int t, int hd, int s, int half, const float* stage) {
;     ...
;   } else if (KIND == G_IN1) {
;     tile_map(t, 64, 68, pm, pn);
;     const int col0 = pn * 256;
;     if (col0 < 8192) {
;       const int b = pm >> 5, t0 = (pm & 31) * 256 + hr;
;       emit_tr(stage, (u16*)(ws + OFF_XMT) + ((long)b * 8192 + col0) * SEQ + t0, SEQ);
;     } else if (col0 < 16384) {
;       emit_rm(stage, (u16*)(ws + OFF_CAT1) + ((long)pm * 256 + hr) * 8704 + (col0 - 8192), 8704, nullptr);
;     } else {
;       emit_rm(stage, (u16*)(ws + OFF_MQG) + ((long)pm * 256 + hr) * 1024 + (col0 - 16384), 1024, nullptr);
;     }
.LBB0_146:
	s_ashr_i32 s0, s17, 31
	s_lshr_b32 s0, s0, 29
	s_add_i32 s0, s17, s0
	s_ashr_i32 s1, s0, 3
	s_and_b32 s0, s0, -8
	s_sub_i32 s0, s17, s0
	s_lshr_b32 s4, s0, 31
	s_or_b32 s4, s4, 0x220
	s_mul_i32 s0, s4, s0
	s_add_i32 s0, s0, s1
	s_mul_hi_i32 s1, s0, 0x78787879
	s_lshr_b32 s4, s1, 31
	s_ashr_i32 s1, s1, 8
	s_add_i32 s1, s1, s4
	s_lshl_b32 s8, s1, 3
	s_sub_i32 s4, 64, s8
	s_min_i32 s4, s4, 8
	s_abs_i32 s5, s4
	v_cvt_f32_u32_e32 v0, s5
	s_sub_i32 s7, 0, s5
	s_mulk_i32 s1, 0x220
	s_sub_i32 s0, s0, s1
	v_rcp_iflag_f32_e32 v0, v0
	s_abs_i32 s1, s0
	s_xor_b32 s6, s0, s4
	s_ashr_i32 s6, s6, 31
	v_mul_f32_e32 v0, 0x4f7ffffe, v0
	v_cvt_u32_f32_e32 v0, v0
	s_nop 0
	v_readfirstlane_b32 s9, v0
	s_mul_i32 s7, s7, s9
	s_mul_hi_u32 s7, s9, s7
	s_add_i32 s9, s9, s7
	s_mul_hi_u32 s7, s1, s9
	s_mul_i32 s9, s7, s5
	s_sub_i32 s1, s1, s9
	s_add_i32 s10, s7, 1
	s_sub_i32 s9, s1, s5
	s_cmp_ge_u32 s1, s5
	s_cselect_b32 s7, s10, s7
	s_cselect_b32 s1, s9, s1
	s_add_i32 s9, s7, 1
	s_cmp_ge_u32 s1, s5
	s_cselect_b32 s1, s9, s7
	s_xor_b32 s1, s1, s6
	s_sub_i32 s9, s1, s6
	s_mul_i32 s1, s9, s4
	s_sub_i32 s10, s0, s1
	s_cmp_gt_i32 s9, 31
	s_mov_b64 s[0:1], -1
	s_cbranch_scc0 .LBB0_162
	v_mov_b32_e32 v0, v139
	v_mov_b32_e32 v2, v139
	s_add_i32 s0, s8, s10
	v_lshrrev_b32_e32 v132, 2, v0
	v_and_b32_e32 v3, 15, v2
	v_and_b32_e32 v132, 0xfffffc0, v132
	v_lshrrev_b32_e32 v2, 2, v2
	v_lshlrev_b32_e32 v0, 1, v0
	v_and_or_b32 v2, v2, 12, v132
	v_and_b32_e32 v0, 0x180, v0
	v_add_u32_e32 v0, 16, v0
	v_lshlrev_b32_e32 v3, 2, v3
	v_mul_lo_u32 v2, v2, s81
	v_add3_u32 v0, v0, v3, v2
	s_lshl_b32 s52, s9, 8
	v_add_u32_e32 v141, 0x8000, v0
	v_add_u32_e32 v144, 0xc000, v0
	s_cmp_gt_u32 s9, 63
	v_add_u32_e32 v2, 0x400, v0
	v_add_u32_e32 v3, 0x800, v0
	v_add_u32_e32 v132, 0xc00, v0
	v_add_u32_e32 v133, 0x4000, v0
	v_add_u32_e32 v134, 0x4400, v0
	v_add_u32_e32 v135, 0x4800, v0
	v_add_u32_e32 v136, 0x4c00, v0
	ds_write2_b32 v141, v112, v108 offset0:128 offset1:144
	v_add_u32_e32 v141, 0x8400, v0
	v_add_u32_e32 v142, 0x8800, v0
	v_add_u32_e32 v143, 0x8c00, v0
	ds_write2_b32 v144, v104, v100 offset0:192 offset1:208
	v_add_u32_e32 v144, 0xc400, v0
	v_add_u32_e32 v145, 0xc800, v0
	v_add_u32_e32 v146, 0xcc00, v0
	s_cselect_b64 s[4:5], -1, 0
	ds_write2_b32 v0, v128, v124 offset1:16
	ds_write2_b32 v2, v129, v125 offset0:4 offset1:20
	ds_write2_b32 v3, v130, v126 offset0:8 offset1:24
	ds_write2_b32 v132, v131, v127 offset0:12 offset1:28
	ds_write2_b32 v133, v120, v116 offset0:64 offset1:80
	ds_write2_b32 v134, v121, v117 offset0:68 offset1:84
	ds_write2_b32 v135, v122, v118 offset0:72 offset1:88
	ds_write2_b32 v136, v123, v119 offset0:76 offset1:92
	ds_write2_b32 v141, v113, v109 offset0:132 offset1:148
	ds_write2_b32 v142, v114, v110 offset0:136 offset1:152
	ds_write2_b32 v143, v115, v111 offset0:140 offset1:156
	ds_write2_b32 v144, v105, v101 offset0:196 offset1:212
	ds_write2_b32 v145, v106, v102 offset0:200 offset1:216
	ds_write2_b32 v146, v107, v103 offset0:204 offset1:220
	ds_write2_b32 v0, v96, v92 offset0:128 offset1:144
	ds_write2_b32 v2, v97, v93 offset0:132 offset1:148
	ds_write2_b32 v3, v98, v94 offset0:136 offset1:152
	ds_write2_b32 v132, v99, v95 offset0:140 offset1:156
	ds_write2_b32 v133, v88, v84 offset0:192 offset1:208
	ds_write2_b32 v134, v89, v85 offset0:196 offset1:212
	ds_write2_b32 v135, v90, v86 offset0:200 offset1:216
	ds_write2_b32 v136, v91, v87 offset0:204 offset1:220
	ds_write2_b32 v141, v80, v76 offset1:16
	ds_write2_b32 v142, v81, v77 offset0:4 offset1:20
	ds_write2_b32 v143, v82, v78 offset0:8 offset1:24
	v_add_u32_e32 v2, 0x9000, v0
	v_add_u32_e32 v0, 0xd000, v0
	s_ashr_i32 s1, s0, 31
	s_mov_b64 s[6:7], -1
	s_and_b64 vcc, exec, s[4:5]
	ds_write2_b32 v2, v83, v79 offset0:12 offset1:28
	ds_write2_b32 v144, v72, v68 offset0:64 offset1:80
	ds_write2_b32 v145, v73, v69 offset0:68 offset1:84
	ds_write2_b32 v146, v74, v70 offset0:72 offset1:88
	ds_write2_b32 v0, v75, v71 offset0:76 offset1:92
	s_waitcnt lgkmcnt(0)
	s_barrier
	s_cbranch_vccz .LBB0_151
	v_mov_b32_e32 v0, v139
	s_lshl_b64 s[6:7], s[0:1], 19
	v_ashrrev_i32_e32 v132, 5, v0
	v_ashrrev_i32_e32 v133, 31, v132
	v_lshlrev_b64 v[2:3], 11, v[132:133]
	v_lshl_add_u64 v[2:3], s[6:7], 0, v[2:3]
	s_lshl_b64 s[6:7], s[52:53], 1
	v_and_b32_e32 v0, 31, v0
	s_add_u32 s6, s66, s6
	v_lshl_or_b32 v2, v0, 3, v2
	s_addc_u32 s7, s67, s7
	v_mul_lo_u32 v132, v132, s81
	v_lshlrev_b32_e32 v0, 4, v0
	v_lshl_add_u64 v[2:3], s[6:7], 0, v[2:3]
	v_add3_u32 v0, v132, v0, 16
	s_mov_b64 s[6:7], 0
	ds_read_b128 v[232:235], v0
	ds_read_b128 v[236:239], v0 offset:512
.LBB0_149:
	s_mov_b32 s11, 0x317f8000
	v_add_u32_e32 v0, 0x4100, v0
	s_waitcnt lgkmcnt(0)
	v_cvt_pk_bf16_f32 v132, v232, v233
	v_cvt_pk_bf16_f32 v133, v234, v235
	s_waitcnt lgkmcnt(0)
	v_cvt_pk_bf16_f32 v134, v236, v237
	v_lshl_add_u64 v[142:143], v[2:3], 0, s[6:7]
	s_add_u32 s6, s6, 0x8000
	v_add_co_u32_e32 v142, vcc, s11, v142
	s_addc_u32 s7, s7, 0
	s_nop 0
	v_addc_co_u32_e32 v143, vcc, 0, v143, vcc
	s_cmp_lg_u32 s6, 0x40000
	v_cvt_pk_bf16_f32 v135, v238, v239
	ds_read_b128 v[232:235], v0
	ds_read_b128 v[236:239], v0 offset:512
	global_store_dwordx2 v[142:143], v[132:133], off
	global_store_dwordx2 v[142:143], v[134:135], off offset:256
	s_cbranch_scc1 .LBB0_149
	s_mov_b64 s[6:7], 0
.LBB0_151:
	s_and_b64 vcc, exec, s[6:7]
	s_cbranch_vccz .LBB0_154
	v_mov_b32_e32 v0, v139
	s_movk_i32 s6, 0x4400
	v_ashrrev_i32_e32 v132, 5, v0
	v_mad_i64_i32 v[2:3], s[6:7], v132, s6, 0
	v_mad_i64_i32 v[2:3], s[6:7], s0, v205, v[2:3]
	s_lshl_b64 s[6:7], s[52:53], 1
	v_and_b32_e32 v0, 31, v0
	s_add_u32 s6, s66, s6
	v_lshl_or_b32 v2, v0, 3, v2
	s_addc_u32 s7, s67, s7
	v_mul_lo_u32 v132, v132, s81
	v_lshlrev_b32_e32 v0, 4, v0
	v_lshl_add_u64 v[2:3], s[6:7], 0, v[2:3]
	v_add3_u32 v0, v132, v0, 16
	s_mov_b64 s[6:7], 0
	ds_read_b128 v[232:235], v0
	ds_read_b128 v[236:239], v0 offset:512
; __device__ __forceinline__ int ltid() { int t = threadIdx.x; asm volatile("" : "+v"(t)); return t; }
; template <int AI>
; __device__ __forceinline__ void dump_half(const f32x4 (&acc)[2][2][4][2], float* stage) {
;   const int wid = ltid() >> 6, lane = ltid() & 63, wr = wid >> 2, wc = wid & 3, fr = lane & 15, fq = lane >> 4;
; #pragma unroll
;   for (int bj = 0; bj < 2; ++bj)
; #pragma unroll
;     for (int m = 0; m < 4; ++m)
; #pragma unroll
;       for (int n = 0; n < 2; ++n) {
;         const int r0 = wr * 64 + m * 16 + fq * 4, c = bj * 128 + wc * 32 + n * 16 + fr;
; #pragma unroll
;         for (int j = 0; j < 4; ++j) stage[(r0 + j) * SP + c] = acc[AI][bj][m][n][j];
;       }
; }
; __device__ __forceinline__ void emit_rm(const float* stage, u16* dst, long ld, const float* rs) {
;   const int tid = ltid(), c4 = (tid & 31) * 4, rr = tid >> 5;
; #pragma unroll 1
;   for (int ps = 0; ps < 8; ++ps) {
;     const int r = ps * 16 + rr;
;     const float* s = stage + r * SP + c4;
;     const float4 a = *(const float4*)s, b = *(const float4*)(s + 128);
;     const float f = rs ? rs[r] : 1.f;
;     uint2 o0, o1;
;     o0.x = pack2(a.x * f, a.y * f); o0.y = pack2(a.z * f, a.w * f);
;     o1.x = pack2(b.x * f, b.y * f); o1.y = pack2(b.z * f, b.w * f);
;     *(uint2*)(dst + (long)r * ld + c4) = o0;
;     *(uint2*)(dst + (long)r * ld + 128 + c4) = o1;
;   }
; }
; template <int KIND>
; __device__ __forceinline__ void tile_emit(const Ctx& p, int t, int hd, int s, int half, const float* stage) {
;     ...
;     } else if (col0 < 16384) {
;       emit_rm(stage, (u16*)(ws + OFF_CAT1) + ((long)pm * 256 + hr) * 8704 + (col0 - 8192), 8704, nullptr);
;     } else {
;       emit_rm(stage, (u16*)(ws + OFF_MQG) + ((long)pm * 256 + hr) * 1024 + (col0 - 16384), 1024, nullptr);
;     }
.LBB0_153:
	s_mov_b32 s11, 0x207fc000
	v_add_u32_e32 v0, 0x4100, v0
	s_waitcnt lgkmcnt(0)
	v_cvt_pk_bf16_f32 v132, v232, v233
	v_cvt_pk_bf16_f32 v133, v234, v235
	v_cvt_pk_bf16_f32 v134, v236, v237
	v_lshl_add_u64 v[142:143], v[2:3], 0, s[6:7]
	s_add_u32 s6, s6, 0x44000
	v_add_co_u32_e32 v142, vcc, s11, v142
	s_addc_u32 s7, s7, 0
	s_nop 0
	v_addc_co_u32_e32 v143, vcc, 0, v143, vcc
	s_cmp_eq_u32 s6, 0x220000
	v_cvt_pk_bf16_f32 v135, v238, v239
	ds_read_b128 v[232:235], v0
	ds_read_b128 v[236:239], v0 offset:512
	global_store_dwordx2 v[142:143], v[132:133], off
	global_store_dwordx2 v[142:143], v[134:135], off offset:256
	s_cbranch_scc0 .LBB0_153
.LBB0_154:
	v_mov_b32_e32 v0, v139
	v_mov_b32_e32 v2, v139
	s_waitcnt lgkmcnt(0)
	s_barrier
	s_mov_b64 s[6:7], -1
	v_lshrrev_b32_e32 v132, 2, v0
	v_and_b32_e32 v3, 15, v2
	v_and_b32_e32 v132, 0xfffffc0, v132
	v_lshrrev_b32_e32 v2, 2, v2
	v_lshlrev_b32_e32 v0, 1, v0
	v_and_or_b32 v2, v2, 12, v132
	v_and_b32_e32 v0, 0x180, v0
	v_add_u32_e32 v0, 16, v0
	v_lshlrev_b32_e32 v3, 2, v3
	v_mul_lo_u32 v2, v2, s81
	v_add3_u32 v0, v0, v3, v2
	v_add_u32_e32 v141, 0x8000, v0
	v_add_u32_e32 v144, 0xc000, v0
	v_add_u32_e32 v2, 0x400, v0
	v_add_u32_e32 v3, 0x800, v0
	v_add_u32_e32 v132, 0xc00, v0
	v_add_u32_e32 v133, 0x4000, v0
	v_add_u32_e32 v134, 0x4400, v0
	v_add_u32_e32 v135, 0x4800, v0
	v_add_u32_e32 v136, 0x4c00, v0
	ds_write2_b32 v141, v48, v44 offset0:128 offset1:144
	v_add_u32_e32 v141, 0x8400, v0
	v_add_u32_e32 v142, 0x8800, v0
	v_add_u32_e32 v143, 0x8c00, v0
	ds_write2_b32 v144, v40, v36 offset0:192 offset1:208
	v_add_u32_e32 v144, 0xc400, v0
	v_add_u32_e32 v145, 0xc800, v0
	v_add_u32_e32 v146, 0xcc00, v0
	ds_write2_b32 v0, v64, v60 offset1:16
	ds_write2_b32 v2, v65, v61 offset0:4 offset1:20
	ds_write2_b32 v3, v66, v62 offset0:8 offset1:24
	ds_write2_b32 v132, v67, v63 offset0:12 offset1:28
	ds_write2_b32 v133, v56, v52 offset0:64 offset1:80
	ds_write2_b32 v134, v57, v53 offset0:68 offset1:84
	ds_write2_b32 v135, v58, v54 offset0:72 offset1:88
	ds_write2_b32 v136, v59, v55 offset0:76 offset1:92
	ds_write2_b32 v141, v49, v45 offset0:132 offset1:148
	ds_write2_b32 v142, v50, v46 offset0:136 offset1:152
	ds_write2_b32 v143, v51, v47 offset0:140 offset1:156
	ds_write2_b32 v144, v41, v37 offset0:196 offset1:212
	ds_write2_b32 v145, v42, v38 offset0:200 offset1:216
	ds_write2_b32 v146, v43, v39 offset0:204 offset1:220
	ds_write2_b32 v0, v32, v28 offset0:128 offset1:144
	ds_write2_b32 v2, v33, v29 offset0:132 offset1:148
	ds_write2_b32 v3, v34, v30 offset0:136 offset1:152
	ds_write2_b32 v132, v35, v31 offset0:140 offset1:156
	ds_write2_b32 v133, v24, v20 offset0:192 offset1:208
	ds_write2_b32 v134, v25, v21 offset0:196 offset1:212
	ds_write2_b32 v135, v26, v22 offset0:200 offset1:216
	ds_write2_b32 v136, v27, v23 offset0:204 offset1:220
	ds_write2_b32 v141, v16, v12 offset1:16
	ds_write2_b32 v142, v17, v13 offset0:4 offset1:20
	ds_write2_b32 v143, v18, v14 offset0:8 offset1:24
	v_add_u32_e32 v2, 0x9000, v0
	v_add_u32_e32 v0, 0xd000, v0
	s_and_b64 vcc, exec, s[4:5]
	ds_write2_b32 v2, v19, v15 offset0:12 offset1:28
	ds_write2_b32 v144, v8, v4 offset0:64 offset1:80
	ds_write2_b32 v145, v9, v5 offset0:68 offset1:84
	ds_write2_b32 v146, v10, v6 offset0:72 offset1:88
	ds_write2_b32 v0, v11, v7 offset0:76 offset1:92
	s_waitcnt lgkmcnt(0)
	s_barrier
	s_cbranch_vccz .LBB0_158
	v_mov_b32_e32 v0, v139
	s_lshl_b64 s[4:5], s[0:1], 19
	v_ashrrev_i32_e32 v132, 5, v0
	v_ashrrev_i32_e32 v133, 31, v132
	v_lshlrev_b64 v[2:3], 11, v[132:133]
	v_lshl_add_u64 v[2:3], s[4:5], 0, v[2:3]
	s_lshl_b64 s[4:5], s[52:53], 1
	v_and_b32_e32 v0, 31, v0
	s_add_u32 s4, s66, s4
	v_lshl_or_b32 v2, v0, 3, v2
	s_addc_u32 s5, s67, s5
	v_mul_lo_u32 v132, v132, s81
	v_lshlrev_b32_e32 v0, 4, v0
	v_lshl_add_u64 v[2:3], s[4:5], 0, v[2:3]
	v_add3_u32 v0, v132, v0, 16
	s_mov_b64 s[4:5], 0
	ds_read_b128 v[232:235], v0
	ds_read_b128 v[236:239], v0 offset:512
.LBB0_156:
	s_mov_b32 s1, 0x31838000
	v_add_u32_e32 v0, 0x4100, v0
	s_waitcnt lgkmcnt(0)
	v_cvt_pk_bf16_f32 v132, v232, v233
	v_cvt_pk_bf16_f32 v133, v234, v235
	v_cvt_pk_bf16_f32 v134, v236, v237
	v_lshl_add_u64 v[142:143], v[2:3], 0, s[4:5]
	s_add_u32 s4, s4, 0x8000
	v_add_co_u32_e32 v142, vcc, s1, v142
	s_addc_u32 s5, s5, 0
	s_nop 0
	v_addc_co_u32_e32 v143, vcc, 0, v143, vcc
	s_cmp_lg_u32 s4, 0x40000
	v_cvt_pk_bf16_f32 v135, v238, v239
	ds_read_b128 v[232:235], v0
	ds_read_b128 v[236:239], v0 offset:512
	global_store_dwordx2 v[142:143], v[132:133], off
	global_store_dwordx2 v[142:143], v[134:135], off offset:256
	s_cbranch_scc1 .LBB0_156
	s_mov_b64 s[6:7], 0
.LBB0_158:
	s_and_b64 vcc, exec, s[6:7]
	s_cbranch_vccz .LBB0_161
	v_mov_b32_e32 v0, v139
	s_movk_i32 s1, 0x4400
	v_ashrrev_i32_e32 v132, 5, v0
	v_mad_i64_i32 v[2:3], s[4:5], v132, s1, 0
	v_mad_i64_i32 v[2:3], s[0:1], s0, v205, v[2:3]
	s_lshl_b64 s[0:1], s[52:53], 1
	v_and_b32_e32 v0, 31, v0
	s_add_u32 s0, s66, s0
	v_lshl_or_b32 v2, v0, 3, v2
	s_addc_u32 s1, s67, s1
	v_mul_lo_u32 v132, v132, s81
	v_lshlrev_b32_e32 v0, 4, v0
	v_lshl_add_u64 v[2:3], s[0:1], 0, v[2:3]
	v_add3_u32 v0, v132, v0, 16
	s_mov_b64 s[0:1], 0
	ds_read_b128 v[232:235], v0
	ds_read_b128 v[236:239], v0 offset:512
.LBB0_160:
	s_mov_b32 s4, 0x20a1c000
	v_add_u32_e32 v0, 0x4100, v0
	s_waitcnt lgkmcnt(0)
	v_cvt_pk_bf16_f32 v132, v232, v233
	v_cvt_pk_bf16_f32 v133, v234, v235
	v_cvt_pk_bf16_f32 v134, v236, v237
	v_lshl_add_u64 v[142:143], v[2:3], 0, s[0:1]
	s_add_u32 s0, s0, 0x44000
	v_add_co_u32_e32 v142, vcc, s4, v142
	s_addc_u32 s1, s1, 0
	s_nop 0
	v_addc_co_u32_e32 v143, vcc, 0, v143, vcc
	s_cmp_eq_u32 s0, 0x220000
	v_cvt_pk_bf16_f32 v135, v238, v239
	ds_read_b128 v[232:235], v0
	ds_read_b128 v[236:239], v0 offset:512
	global_store_dwordx2 v[142:143], v[132:133], off
	global_store_dwordx2 v[142:143], v[134:135], off offset:256
	s_cbranch_scc0 .LBB0_160

; __device__ __forceinline__ int ltid() { int t = threadIdx.x; asm volatile("" : "+v"(t)); return t; }
; template <int AI>
; __device__ __forceinline__ void dump_half(const f32x4 (&acc)[2][2][4][2], float* stage) {
;   const int wid = ltid() >> 6, lane = ltid() & 63, wr = wid >> 2, wc = wid & 3, fr = lane & 15, fq = lane >> 4;
; #pragma unroll
;   for (int bj = 0; bj < 2; ++bj)
; #pragma unroll
;     for (int m = 0; m < 4; ++m)
; #pragma unroll
;       for (int n = 0; n < 2; ++n) {
;         const int r0 = wr * 64 + m * 16 + fq * 4, c = bj * 128 + wc * 32 + n * 16 + fr;
; #pragma unroll
;         for (int j = 0; j < 4; ++j) stage[(r0 + j) * SP + c] = acc[AI][bj][m][n][j];
;       }
; template <int KIND>
; __device__ __forceinline__ void tile_emit(const Ctx& p, int t, int hd, int s, int half, const float* stage) {
;     ...
;   } else if (KIND == G_OUT0 || KIND == G_OUT1) {
;     tile_map(t, 64, 16, pm, pn);
;     u16* yb = (u16*)(ws + (KIND == G_OUT0 ? OFF_Y0 : OFF_Y1));
;     emit_rm(stage, yb + ((long)pm * 256 + hr) * DM + pn * 256, DM, nullptr);
.LBB0_207:
	v_mov_b32_e32 v0, v139
	v_mov_b32_e32 v2, v139
	s_ashr_i32 s0, s13, 31
	v_lshrrev_b32_e32 v132, 2, v0
	v_and_b32_e32 v3, 15, v2
	v_and_b32_e32 v132, 0xfffffc0, v132
	v_lshrrev_b32_e32 v2, 2, v2
	v_lshlrev_b32_e32 v0, 1, v0
	v_and_or_b32 v2, v2, 12, v132
	v_and_b32_e32 v0, 0x180, v0
	v_add_u32_e32 v0, 16, v0
	v_lshlrev_b32_e32 v3, 2, v3
	v_mul_lo_u32 v2, v2, s81
	s_lshr_b32 s0, s0, 29
	v_add3_u32 v0, v0, v3, v2
	s_add_i32 s0, s13, s0
	v_add_u32_e32 v2, 0x400, v0
	s_ashr_i32 s1, s0, 3
	s_and_b32 s0, s0, -8
	ds_write2_b32 v2, v129, v125 offset0:4 offset1:20
	v_add_u32_e32 v125, 0x4000, v0
	s_sub_i32 s0, s13, s0
	ds_write2_b32 v125, v120, v116 offset0:64 offset1:80
	v_add_u32_e32 v116, 0x4400, v0
	s_lshr_b32 s4, s0, 31
	ds_write2_b32 v116, v121, v117 offset0:68 offset1:84
	v_add_u32_e32 v117, 0x4800, v0
	s_bitset1_b32 s4, 7
	ds_write2_b32 v117, v122, v118 offset0:72 offset1:88
	v_add_u32_e32 v118, 0x4c00, v0
	s_mul_i32 s0, s4, s0
	ds_write2_b32 v118, v123, v119 offset0:76 offset1:92
	v_add_u32_e32 v119, 0x8000, v0
	s_add_i32 s0, s0, s1
	ds_write2_b32 v119, v112, v108 offset0:128 offset1:144
	v_add_u32_e32 v108, 0x8400, v0
	s_ashr_i32 s1, s0, 31
	ds_write2_b32 v108, v113, v109 offset0:132 offset1:148
	v_add_u32_e32 v109, 0x8800, v0
	s_lshr_b32 s1, s1, 25
	ds_write2_b32 v109, v114, v110 offset0:136 offset1:152
	v_add_u32_e32 v110, 0x8c00, v0
	s_add_i32 s1, s0, s1
	ds_write2_b32 v110, v115, v111 offset0:140 offset1:156
	v_add_u32_e32 v111, 0xc000, v0
	s_ashr_i32 s4, s1, 7
	ds_write2_b32 v111, v104, v100 offset0:192 offset1:208
	v_add_u32_e32 v100, 0xc400, v0
	s_lshl_b32 s4, s4, 3
	ds_write2_b32 v100, v105, v101 offset0:196 offset1:212
	v_add_u32_e32 v101, 0xc800, v0
	s_sub_i32 s5, 64, s4
	ds_write2_b32 v0, v128, v124 offset1:16
	v_add_u32_e32 v3, 0x800, v0
	v_add_u32_e32 v124, 0xc00, v0
	ds_write2_b32 v101, v106, v102 offset0:200 offset1:216
	v_add_u32_e32 v102, 0xcc00, v0
	s_min_i32 s5, s5, 8
	ds_write2_b32 v3, v130, v126 offset0:8 offset1:24
	ds_write2_b32 v124, v131, v127 offset0:12 offset1:28
	ds_write2_b32 v102, v107, v103 offset0:204 offset1:220
	ds_write2_b32 v0, v96, v92 offset0:128 offset1:144
	ds_write2_b32 v2, v97, v93 offset0:132 offset1:148
	ds_write2_b32 v3, v98, v94 offset0:136 offset1:152
	ds_write2_b32 v124, v99, v95 offset0:140 offset1:156
	ds_write2_b32 v125, v88, v84 offset0:192 offset1:208
	ds_write2_b32 v116, v89, v85 offset0:196 offset1:212
	ds_write2_b32 v117, v90, v86 offset0:200 offset1:216
	ds_write2_b32 v118, v91, v87 offset0:204 offset1:220
	ds_write2_b32 v108, v80, v76 offset1:16
	ds_write2_b32 v109, v81, v77 offset0:4 offset1:20
	ds_write2_b32 v110, v82, v78 offset0:8 offset1:24
	v_add_u32_e32 v2, 0x9000, v0
	v_add_u32_e32 v0, 0xd000, v0
	s_abs_i32 s6, s5
	ds_write2_b32 v2, v83, v79 offset0:12 offset1:28
	ds_write2_b32 v100, v72, v68 offset0:64 offset1:80
	ds_write2_b32 v101, v73, v69 offset0:68 offset1:84
	ds_write2_b32 v102, v74, v70 offset0:72 offset1:88
	ds_write2_b32 v0, v75, v71 offset0:76 offset1:92
	v_cvt_f32_u32_e32 v0, s6
	s_sub_i32 s13, 0, s6
	s_and_b32 s1, s1, 0xffffff80
	s_sub_i32 s0, s0, s1
	v_rcp_iflag_f32_e32 v0, v0
	s_abs_i32 s7, s0
	s_xor_b32 s1, s0, s5
	s_ashr_i32 s1, s1, 31
	v_mul_f32_e32 v0, 0x4f7ffffe, v0
	v_cvt_u32_f32_e32 v0, v0
	s_waitcnt lgkmcnt(0)
	s_barrier
	v_readfirstlane_b32 s14, v0
	s_mul_i32 s13, s13, s14
	s_mul_hi_u32 s13, s14, s13
	s_add_i32 s14, s14, s13
	s_mul_hi_u32 s13, s7, s14
	s_mul_i32 s14, s13, s6
	s_sub_i32 s7, s7, s14
	s_add_i32 s14, s13, 1
	s_sub_i32 s15, s7, s6
	s_cmp_ge_u32 s7, s6
	s_cselect_b32 s13, s14, s13
	s_cselect_b32 s7, s15, s7
	s_add_i32 s14, s13, 1
	s_cmp_ge_u32 s7, s6
	s_cselect_b32 s6, s14, s13
	s_xor_b32 s6, s6, s1
	s_sub_i32 s6, s6, s1
	s_mul_i32 s1, s6, s5
	s_sub_i32 s0, s0, s1
	v_mov_b32_e32 v0, v139
	s_add_i32 s0, s0, s4
	s_lshl_b32 s4, s6, 8
	s_ashr_i32 s1, s0, 31
	v_ashrrev_i32_e32 v68, 5, v0
	s_ashr_i32 s5, s4, 31
	v_ashrrev_i32_e32 v69, 31, v68
	s_lshl_b64 s[0:1], s[0:1], 21
	v_lshlrev_b64 v[2:3], 13, v[68:69]
	s_lshl_b64 s[4:5], s[4:5], 1
	v_lshl_add_u64 v[2:3], s[0:1], 0, v[2:3]
	v_and_b32_e32 v0, 31, v0
	s_add_u32 s6, s66, s4
	v_lshl_or_b32 v2, v0, 3, v2
	s_addc_u32 s7, s67, s5
	v_mul_lo_u32 v68, v68, s81
	v_lshlrev_b32_e32 v0, 4, v0
	v_lshl_add_u64 v[2:3], s[6:7], 0, v[2:3]
	v_add3_u32 v0, v68, v0, 16
	s_mov_b64 s[6:7], 0
	ds_read_b128 v[232:235], v0
	ds_read_b128 v[236:239], v0 offset:512
; __device__ __forceinline__ int ltid() { int t = threadIdx.x; asm volatile("" : "+v"(t)); return t; }
; template <int AI>
; __device__ __forceinline__ void dump_half(const f32x4 (&acc)[2][2][4][2], float* stage) {
;   const int wid = ltid() >> 6, lane = ltid() & 63, wr = wid >> 2, wc = wid & 3, fr = lane & 15, fq = lane >> 4;
; #pragma unroll
;   for (int bj = 0; bj < 2; ++bj)
; #pragma unroll
;     for (int m = 0; m < 4; ++m)
; #pragma unroll
;       for (int n = 0; n < 2; ++n) {
;         const int r0 = wr * 64 + m * 16 + fq * 4, c = bj * 128 + wc * 32 + n * 16 + fr;
; #pragma unroll
;         for (int j = 0; j < 4; ++j) stage[(r0 + j) * SP + c] = acc[AI][bj][m][n][j];
;       }
; }
; __device__ __forceinline__ void emit_rm(const float* stage, u16* dst, long ld, const float* rs) {
;   const int tid = ltid(), c4 = (tid & 31) * 4, rr = tid >> 5;
; #pragma unroll 1
;   for (int ps = 0; ps < 8; ++ps) {
;     const int r = ps * 16 + rr;
;     const float* s = stage + r * SP + c4;
;     const float4 a = *(const float4*)s, b = *(const float4*)(s + 128);
;     const float f = rs ? rs[r] : 1.f;
;     uint2 o0, o1;
;     o0.x = pack2(a.x * f, a.y * f); o0.y = pack2(a.z * f, a.w * f);
;     o1.x = pack2(b.x * f, b.y * f); o1.y = pack2(b.z * f, b.w * f);
;     *(uint2*)(dst + (long)r * ld + c4) = o0;
;     *(uint2*)(dst + (long)r * ld + 128 + c4) = o1;
;   }
; }
; template <int KIND>
; __device__ __forceinline__ void tile_emit(const Ctx& p, int t, int hd, int s, int half, const float* stage) {
;     ...
;   } else if (KIND == G_OUT0 || KIND == G_OUT1) {
;     tile_map(t, 64, 16, pm, pn);
;     u16* yb = (u16*)(ws + (KIND == G_OUT0 ? OFF_Y0 : OFF_Y1));
;     emit_rm(stage, yb + ((long)pm * 256 + hr) * DM + pn * 256, DM, nullptr);
.LBB0_208:
	s_mov_b32 s13, 0x12c00000
	v_add_u32_e32 v0, 0x4100, v0
	s_waitcnt lgkmcnt(0)
	v_cvt_pk_bf16_f32 v68, v232, v233
	v_cvt_pk_bf16_f32 v69, v234, v235
	s_waitcnt lgkmcnt(0)
	v_cvt_pk_bf16_f32 v70, v236, v237
	v_lshl_add_u64 v[72:73], v[2:3], 0, s[6:7]
	s_add_u32 s6, s6, 0x20000
	v_add_co_u32_e32 v72, vcc, s13, v72
	s_addc_u32 s7, s7, 0
	s_nop 0
	v_addc_co_u32_e32 v73, vcc, 0, v73, vcc
	s_cmp_lg_u32 s6, 0x100000
	v_cvt_pk_bf16_f32 v71, v238, v239
	ds_read_b128 v[232:235], v0
	ds_read_b128 v[236:239], v0 offset:512
	global_store_dwordx2 v[72:73], v[68:69], off
	global_store_dwordx2 v[72:73], v[70:71], off offset:256
	s_cbranch_scc1 .LBB0_208
	v_mov_b32_e32 v0, v139
	v_mov_b32_e32 v2, v139
	s_waitcnt lgkmcnt(0)
	s_barrier
	s_nop 0
	v_lshrrev_b32_e32 v68, 2, v0
	v_and_b32_e32 v3, 15, v2
	v_and_b32_e32 v68, 0xfffffc0, v68
	v_lshrrev_b32_e32 v2, 2, v2
	v_lshlrev_b32_e32 v0, 1, v0
	v_and_or_b32 v2, v2, 12, v68
	v_and_b32_e32 v0, 0x180, v0
	v_add_u32_e32 v0, 16, v0
	v_lshlrev_b32_e32 v3, 2, v3
	v_mul_lo_u32 v2, v2, s81
	v_add3_u32 v0, v0, v3, v2
	v_add_u32_e32 v2, 0x400, v0
	ds_write2_b32 v2, v65, v61 offset0:4 offset1:20
	v_add_u32_e32 v61, 0x4000, v0
	ds_write2_b32 v61, v56, v52 offset0:64 offset1:80
	v_add_u32_e32 v52, 0x4400, v0
	ds_write2_b32 v52, v57, v53 offset0:68 offset1:84
	v_add_u32_e32 v53, 0x4800, v0
	ds_write2_b32 v53, v58, v54 offset0:72 offset1:88
	v_add_u32_e32 v54, 0x4c00, v0
	ds_write2_b32 v54, v59, v55 offset0:76 offset1:92
	v_add_u32_e32 v55, 0x8000, v0
	ds_write2_b32 v55, v48, v44 offset0:128 offset1:144
	v_add_u32_e32 v44, 0x8400, v0
	ds_write2_b32 v44, v49, v45 offset0:132 offset1:148
	v_add_u32_e32 v45, 0x8800, v0
	ds_write2_b32 v45, v50, v46 offset0:136 offset1:152
	v_add_u32_e32 v46, 0x8c00, v0
	ds_write2_b32 v46, v51, v47 offset0:140 offset1:156
	v_add_u32_e32 v47, 0xc000, v0
	ds_write2_b32 v47, v40, v36 offset0:192 offset1:208
	v_add_u32_e32 v36, 0xc400, v0
	ds_write2_b32 v36, v41, v37 offset0:196 offset1:212
	v_add_u32_e32 v37, 0xc800, v0
	ds_write2_b32 v0, v64, v60 offset1:16
	v_add_u32_e32 v3, 0x800, v0
	v_add_u32_e32 v60, 0xc00, v0
	ds_write2_b32 v37, v42, v38 offset0:200 offset1:216
	v_add_u32_e32 v38, 0xcc00, v0
	ds_write2_b32 v3, v66, v62 offset0:8 offset1:24
	ds_write2_b32 v60, v67, v63 offset0:12 offset1:28
	ds_write2_b32 v38, v43, v39 offset0:204 offset1:220
	ds_write2_b32 v0, v32, v28 offset0:128 offset1:144
	ds_write2_b32 v2, v33, v29 offset0:132 offset1:148
	ds_write2_b32 v3, v34, v30 offset0:136 offset1:152
	ds_write2_b32 v60, v35, v31 offset0:140 offset1:156
	ds_write2_b32 v61, v24, v20 offset0:192 offset1:208
	ds_write2_b32 v52, v25, v21 offset0:196 offset1:212
	ds_write2_b32 v53, v26, v22 offset0:200 offset1:216
	ds_write2_b32 v54, v27, v23 offset0:204 offset1:220
	ds_write2_b32 v44, v16, v12 offset1:16
	ds_write2_b32 v45, v17, v13 offset0:4 offset1:20
	ds_write2_b32 v46, v18, v14 offset0:8 offset1:24
	v_add_u32_e32 v2, 0x9000, v0
	v_add_u32_e32 v0, 0xd000, v0
	ds_write2_b32 v2, v19, v15 offset0:12 offset1:28
	ds_write2_b32 v36, v8, v4 offset0:64 offset1:80
	ds_write2_b32 v37, v9, v5 offset0:68 offset1:84
	ds_write2_b32 v38, v10, v6 offset0:72 offset1:88
	ds_write2_b32 v0, v11, v7 offset0:76 offset1:92
	v_mov_b32_e32 v0, v139
	s_waitcnt lgkmcnt(0)
	s_barrier
	s_nop 0
	v_ashrrev_i32_e32 v4, 5, v0
	v_ashrrev_i32_e32 v5, 31, v4
	v_lshlrev_b64 v[2:3], 13, v[4:5]
	v_and_b32_e32 v5, 31, v0
	v_lshl_add_u64 v[2:3], s[0:1], 0, v[2:3]
	v_lshlrev_b32_e32 v0, 3, v5
	s_add_u32 s0, s66, s4
	v_lshl_add_u64 v[2:3], v[2:3], 0, v[0:1]
	s_addc_u32 s1, s67, s5
	v_mul_lo_u32 v0, v4, s81
	v_lshlrev_b32_e32 v4, 4, v5
	v_lshl_add_u64 v[2:3], s[0:1], 0, v[2:3]
	v_add3_u32 v0, v0, v4, 16
	s_mov_b64 s[0:1], 0
	ds_read_b128 v[232:235], v0
	ds_read_b128 v[236:239], v0 offset:512
.LBB0_210:
	s_mov_b32 s4, 0x12d00000
	v_add_u32_e32 v0, 0x4100, v0
	s_waitcnt lgkmcnt(0)
	v_cvt_pk_bf16_f32 v4, v232, v233
	v_cvt_pk_bf16_f32 v5, v234, v235
	v_cvt_pk_bf16_f32 v6, v236, v237
	v_lshl_add_u64 v[8:9], v[2:3], 0, s[0:1]
	s_add_u32 s0, s0, 0x20000
	v_add_co_u32_e32 v8, vcc, s4, v8
	s_addc_u32 s1, s1, 0
	s_nop 0
	v_addc_co_u32_e32 v9, vcc, 0, v9, vcc
	s_cmp_lg_u32 s0, 0x100000
	v_cvt_pk_bf16_f32 v7, v238, v239
	ds_read_b128 v[232:235], v0
	ds_read_b128 v[236:239], v0 offset:512
	global_store_dwordx2 v[8:9], v[4:5], off
	global_store_dwordx2 v[8:9], v[6:7], off offset:256
	s_cbranch_scc1 .LBB0_210
	s_add_i32 s12, s12, 1
	s_mul_i32 s0, s12, s96
	s_add_i32 s13, s0, s63
	s_cmpk_gt_i32 s13, 0x3ff
	s_waitcnt lgkmcnt(0)
	s_barrier
	s_cbranch_scc0 .LBB0_199

; __device__ __forceinline__ int ltid() { int t = threadIdx.x; asm volatile("" : "+v"(t)); return t; }
; __device__ __forceinline__ void emit_rm(const float* stage, u16* dst, long ld, const float* rs) {
;   const int tid = ltid(), c4 = (tid & 31) * 4, rr = tid >> 5;
; #pragma unroll 1
;   for (int ps = 0; ps < 8; ++ps) {
;     const int r = ps * 16 + rr;
;     const float* s = stage + r * SP + c4;
;     const float4 a = *(const float4*)s, b = *(const float4*)(s + 128);
;     const float f = rs ? rs[r] : 1.f;
;     uint2 o0, o1;
;     o0.x = pack2(a.x * f, a.y * f); o0.y = pack2(a.z * f, a.w * f);
;     o1.x = pack2(b.x * f, b.y * f); o1.y = pack2(b.z * f, b.w * f);
;     *(uint2*)(dst + (long)r * ld + c4) = o0;
;     *(uint2*)(dst + (long)r * ld + 128 + c4) = o1;
;   }
; }
; template <int KIND>
; __device__ __forceinline__ void tile_emit(const Ctx& p, int t, int hd, int s, int half, const float* stage) {
;     ...
;   } else if (KIND == G_KV) {
;     int tb = t >> 2; pm = (t >> 1) & 1; pn = t & 1;
;     u16* o = (u16*)(ws + OFF_KV + (size_t)tb * 512 * 1024);
;     if (!(tb & 1)) emit_rm(stage, o + ((long)pm * 256 + hr) * 512 + pn * 256, 512, nullptr);
.LBB0_290:
	s_and_b64 vcc, exec, s[6:7]
	s_cbranch_vccz .LBB0_293
	s_lshl_b32 s6, s17, 17
	s_and_b32 s6, s6, 0x40000
	v_mov_b32_e32 v0, v139
	s_add_u32 s6, s0, s6
	s_addc_u32 s7, s1, 0
	v_ashrrev_i32_e32 v68, 5, v0
	s_lshl_b32 s20, s8, 9
	v_ashrrev_i32_e32 v69, 31, v68
	s_add_u32 s6, s20, s6
	v_lshlrev_b64 v[2:3], 10, v[68:69]
	s_addc_u32 s7, 0, s7
	v_and_b32_e32 v69, 31, v0
	v_lshl_add_u64 v[2:3], s[6:7], 0, v[2:3]
	v_lshlrev_b32_e32 v0, 3, v69
	v_lshl_add_u64 v[2:3], v[2:3], 0, v[0:1]
	v_mul_lo_u32 v0, v68, s81
	v_lshlrev_b32_e32 v68, 4, v69
	v_lshl_add_u64 v[2:3], s[66:67], 0, v[2:3]
	v_add3_u32 v0, v0, v68, 16
	s_mov_b64 s[6:7], 0
	ds_read_b128 v[232:235], v0
	ds_read_b128 v[236:239], v0 offset:512
.LBB0_292:
	v_add_u32_e32 v0, 0x4100, v0
	s_waitcnt lgkmcnt(0)
	v_cvt_pk_bf16_f32 v68, v232, v233
	v_cvt_pk_bf16_f32 v69, v234, v235
	v_cvt_pk_bf16_f32 v70, v236, v237
	v_lshl_add_u64 v[72:73], v[2:3], 0, s[6:7]
	s_add_u32 s6, s6, 0x4000
	v_add_co_u32_e32 v72, vcc, s40, v72
	s_addc_u32 s7, s7, 0
	s_nop 0
	v_addc_co_u32_e32 v73, vcc, 0, v73, vcc
	s_cmp_eq_u32 s6, 0x20000
	v_cvt_pk_bf16_f32 v71, v238, v239
	ds_read_b128 v[232:235], v0
	ds_read_b128 v[236:239], v0 offset:512
	global_store_dwordx2 v[72:73], v[68:69], off
	global_store_dwordx2 v[72:73], v[70:71], off offset:256
	s_cbranch_scc0 .LBB0_292

; __device__ __forceinline__ int ltid() { int t = threadIdx.x; asm volatile("" : "+v"(t)); return t; }
; __device__ __forceinline__ void emit_rm(const float* stage, u16* dst, long ld, const float* rs) {
;   const int tid = ltid(), c4 = (tid & 31) * 4, rr = tid >> 5;
; #pragma unroll 1
;   for (int ps = 0; ps < 8; ++ps) {
;     const int r = ps * 16 + rr;
;     const float* s = stage + r * SP + c4;
;     const float4 a = *(const float4*)s, b = *(const float4*)(s + 128);
;     const float f = rs ? rs[r] : 1.f;
;     uint2 o0, o1;
;     o0.x = pack2(a.x * f, a.y * f); o0.y = pack2(a.z * f, a.w * f);
;     o1.x = pack2(b.x * f, b.y * f); o1.y = pack2(b.z * f, b.w * f);
;     *(uint2*)(dst + (long)r * ld + c4) = o0;
;     *(uint2*)(dst + (long)r * ld + 128 + c4) = o1;
;   }
; }
; template <int KIND>
; __device__ __forceinline__ void tile_emit(const Ctx& p, int t, int hd, int s, int half, const float* stage) {
;     ...
;   } else if (KIND == G_KV) {
;     int tb = t >> 2; pm = (t >> 1) & 1; pn = t & 1;
;     u16* o = (u16*)(ws + OFF_KV + (size_t)tb * 512 * 1024);
;     if (!(tb & 1)) emit_rm(stage, o + ((long)pm * 256 + hr) * 512 + pn * 256, 512, nullptr);
.LBB0_297:
	s_and_b64 vcc, exec, s[6:7]
	s_cbranch_vccz .LBB0_277
	s_lshl_b32 s4, s17, 17
	s_and_b32 s4, s4, 0x40000
	v_mov_b32_e32 v0, v139
	s_add_u32 s0, s0, s4
	s_addc_u32 s1, s1, 0
	v_ashrrev_i32_e32 v4, 5, v0
	s_lshl_b32 s4, s8, 9
	v_ashrrev_i32_e32 v5, 31, v4
	s_add_u32 s0, s4, s0
	v_lshlrev_b64 v[2:3], 10, v[4:5]
	s_addc_u32 s1, 0, s1
	v_and_b32_e32 v5, 31, v0
	v_lshl_add_u64 v[2:3], s[0:1], 0, v[2:3]
	v_lshlrev_b32_e32 v0, 3, v5
	v_lshl_add_u64 v[2:3], v[2:3], 0, v[0:1]
	v_mul_lo_u32 v0, v4, s81
	v_lshlrev_b32_e32 v4, 4, v5
	v_lshl_add_u64 v[2:3], s[66:67], 0, v[2:3]
	v_add3_u32 v0, v0, v4, 16
	s_mov_b64 s[0:1], 0
	ds_read_b128 v[232:235], v0
	ds_read_b128 v[236:239], v0 offset:512
.LBB0_299:
	v_add_u32_e32 v0, 0x4100, v0
	s_waitcnt lgkmcnt(0)
	v_cvt_pk_bf16_f32 v4, v232, v233
	v_cvt_pk_bf16_f32 v5, v234, v235
	v_cvt_pk_bf16_f32 v6, v236, v237
	v_lshl_add_u64 v[8:9], v[2:3], 0, s[0:1]
	s_add_u32 s0, s0, 0x4000
	v_add_co_u32_e32 v8, vcc, s41, v8
	s_addc_u32 s1, s1, 0
	s_nop 0
	v_addc_co_u32_e32 v9, vcc, 0, v9, vcc
	s_cmp_eq_u32 s0, 0x20000
	v_cvt_pk_bf16_f32 v7, v238, v239
	ds_read_b128 v[232:235], v0
	ds_read_b128 v[236:239], v0 offset:512
	global_store_dwordx2 v[8:9], v[4:5], off
	global_store_dwordx2 v[8:9], v[6:7], off offset:256
	s_cbranch_scc0 .LBB0_299
	s_branch .LBB0_277

; __device__ __forceinline__ int ltid() { int t = threadIdx.x; asm volatile("" : "+v"(t)); return t; }
; __device__ __forceinline__ void emit_rm(const float* stage, u16* dst, long ld, const float* rs) {
;   const int tid = ltid(), c4 = (tid & 31) * 4, rr = tid >> 5;
; #pragma unroll 1
;   for (int ps = 0; ps < 8; ++ps) {
;     const int r = ps * 16 + rr;
;     const float* s = stage + r * SP + c4;
;     const float4 a = *(const float4*)s, b = *(const float4*)(s + 128);
;     const float f = rs ? rs[r] : 1.f;
;     uint2 o0, o1;
;     o0.x = pack2(a.x * f, a.y * f); o0.y = pack2(a.z * f, a.w * f);
;     o1.x = pack2(b.x * f, b.y * f); o1.y = pack2(b.z * f, b.w * f);
;     *(uint2*)(dst + (long)r * ld + c4) = o0;
;     *(uint2*)(dst + (long)r * ld + 128 + c4) = o1;
;   }
; }
; template <int KIND>
; __device__ __forceinline__ void tile_emit(const Ctx& p, int t, int hd, int s, int half, const float* stage) {
;     ...
;   } else if (KIND == G_KV) {
;     int tb = t >> 2; pm = (t >> 1) & 1; pn = t & 1;
;     u16* o = (u16*)(ws + OFF_KV + (size_t)tb * 512 * 1024);
;     if (!(tb & 1)) emit_rm(stage, o + ((long)pm * 256 + hr) * 512 + pn * 256, 512, nullptr);
.LBB0_315:
	s_and_b64 vcc, exec, s[6:7]
	s_cbranch_vccz .LBB0_318
	s_lshl_b32 s6, s10, 17
	s_and_b32 s6, s6, 0x40000
	v_mov_b32_e32 v0, v139
	s_add_u32 s6, s0, s6
	s_addc_u32 s7, s1, 0
	v_ashrrev_i32_e32 v68, 5, v0
	s_lshl_b32 s13, s8, 9
	v_ashrrev_i32_e32 v69, 31, v68
	s_add_u32 s6, s13, s6
	v_lshlrev_b64 v[2:3], 10, v[68:69]
	s_addc_u32 s7, 0, s7
	v_and_b32_e32 v69, 31, v0
	v_lshl_add_u64 v[2:3], s[6:7], 0, v[2:3]
	v_lshlrev_b32_e32 v0, 3, v69
	v_lshl_add_u64 v[2:3], v[2:3], 0, v[0:1]
	v_mul_lo_u32 v0, v68, s81
	v_lshlrev_b32_e32 v68, 4, v69
	v_lshl_add_u64 v[2:3], s[66:67], 0, v[2:3]
	v_add3_u32 v0, v0, v68, 16
	s_mov_b64 s[6:7], 0
	ds_read_b128 v[232:235], v0
	ds_read_b128 v[236:239], v0 offset:512

; __device__ __forceinline__ int ltid() { int t = threadIdx.x; asm volatile("" : "+v"(t)); return t; }
; __device__ __forceinline__ void emit_rm(const float* stage, u16* dst, long ld, const float* rs) {
;   const int tid = ltid(), c4 = (tid & 31) * 4, rr = tid >> 5;
; #pragma unroll 1
;   for (int ps = 0; ps < 8; ++ps) {
;     const int r = ps * 16 + rr;
;     const float* s = stage + r * SP + c4;
;     const float4 a = *(const float4*)s, b = *(const float4*)(s + 128);
;     const float f = rs ? rs[r] : 1.f;
;     uint2 o0, o1;
;     o0.x = pack2(a.x * f, a.y * f); o0.y = pack2(a.z * f, a.w * f);
;     o1.x = pack2(b.x * f, b.y * f); o1.y = pack2(b.z * f, b.w * f);
;     *(uint2*)(dst + (long)r * ld + c4) = o0;
;     *(uint2*)(dst + (long)r * ld + 128 + c4) = o1;
;   }
; }
; template <int KIND>
; __device__ __forceinline__ void tile_emit(const Ctx& p, int t, int hd, int s, int half, const float* stage) {
;     ...
;   } else if (KIND == G_KV) {
;     int tb = t >> 2; pm = (t >> 1) & 1; pn = t & 1;
;     u16* o = (u16*)(ws + OFF_KV + (size_t)tb * 512 * 1024);
;     if (!(tb & 1)) emit_rm(stage, o + ((long)pm * 256 + hr) * 512 + pn * 256, 512, nullptr);
.LBB0_322:
	s_and_b64 vcc, exec, s[6:7]
	s_cbranch_vccz .LBB0_325
	s_lshl_b32 s4, s10, 17
	s_and_b32 s4, s4, 0x40000
	v_mov_b32_e32 v0, v139
	s_add_u32 s0, s0, s4
	s_addc_u32 s1, s1, 0
	v_ashrrev_i32_e32 v4, 5, v0
	s_lshl_b32 s4, s8, 9
	v_ashrrev_i32_e32 v5, 31, v4
	s_add_u32 s0, s4, s0
	v_lshlrev_b64 v[2:3], 10, v[4:5]
	s_addc_u32 s1, 0, s1
	v_and_b32_e32 v5, 31, v0
	v_lshl_add_u64 v[2:3], s[0:1], 0, v[2:3]
	v_lshlrev_b32_e32 v0, 3, v5
	v_lshl_add_u64 v[2:3], v[2:3], 0, v[0:1]
	v_mul_lo_u32 v0, v4, s81
	v_lshlrev_b32_e32 v4, 4, v5
	v_lshl_add_u64 v[2:3], s[66:67], 0, v[2:3]
	v_add3_u32 v0, v0, v4, 16
	s_mov_b64 s[0:1], 0
	ds_read_b128 v[232:235], v0
	ds_read_b128 v[236:239], v0 offset:512
.LBB0_324:
	v_add_u32_e32 v0, 0x4100, v0
	s_waitcnt lgkmcnt(0)
	v_cvt_pk_bf16_f32 v4, v232, v233
	v_cvt_pk_bf16_f32 v5, v234, v235
	v_cvt_pk_bf16_f32 v6, v236, v237
	v_lshl_add_u64 v[8:9], v[2:3], 0, s[0:1]
	s_add_u32 s0, s0, 0x4000
	v_add_co_u32_e32 v8, vcc, s41, v8
	s_addc_u32 s1, s1, 0
	s_nop 0
	v_addc_co_u32_e32 v9, vcc, 0, v9, vcc
	s_cmp_eq_u32 s0, 0x20000
	v_cvt_pk_bf16_f32 v7, v238, v239
	ds_read_b128 v[232:235], v0
	ds_read_b128 v[236:239], v0 offset:512
	global_store_dwordx2 v[8:9], v[4:5], off
	global_store_dwordx2 v[8:9], v[6:7], off offset:256
	s_cbranch_scc0 .LBB0_324

; __device__ __forceinline__ int ltid() { int t = threadIdx.x; asm volatile("" : "+v"(t)); return t; }
; template <int AI>
; __device__ __forceinline__ void dump_half(const f32x4 (&acc)[2][2][4][2], float* stage) {
;   const int wid = ltid() >> 6, lane = ltid() & 63, wr = wid >> 2, wc = wid & 3, fr = lane & 15, fq = lane >> 4;
; #pragma unroll
;   for (int bj = 0; bj < 2; ++bj)
; #pragma unroll
;     for (int m = 0; m < 4; ++m)
; #pragma unroll
;       for (int n = 0; n < 2; ++n) {
;         const int r0 = wr * 64 + m * 16 + fq * 4, c = bj * 128 + wc * 32 + n * 16 + fr;
; #pragma unroll
;         for (int j = 0; j < 4; ++j) stage[(r0 + j) * SP + c] = acc[AI][bj][m][n][j];
;       }
; template <int KIND>
; __device__ __forceinline__ void tile_emit(const Ctx& p, int t, int hd, int s, int half, const float* stage) {
;     ...
;   if (KIND == G_IN0) {
;     tile_map(t, 64, 60, pm, pn);
;     emit_rm(stage, (u16*)(ws + OFF_H0) + ((long)pm * 256 + hr) * H0LD + pn * 256, H0LD, nullptr);
.LBB0_370:
	v_mov_b32_e32 v0, v139
	v_mov_b32_e32 v2, v139
	s_ashr_i32 s0, s15, 31
	v_lshrrev_b32_e32 v132, 2, v0
	v_and_b32_e32 v3, 15, v2
	v_and_b32_e32 v132, 0xfffffc0, v132
	v_lshrrev_b32_e32 v2, 2, v2
	v_lshlrev_b32_e32 v0, 1, v0
	v_and_or_b32 v2, v2, 12, v132
	v_and_b32_e32 v0, 0x180, v0
	v_add_u32_e32 v0, 16, v0
	v_lshlrev_b32_e32 v3, 2, v3
	v_mul_lo_u32 v2, v2, s81
	s_lshr_b32 s0, s0, 29
	v_add3_u32 v0, v0, v3, v2
	s_add_i32 s0, s15, s0
	v_add_u32_e32 v2, 0x400, v0
	s_ashr_i32 s1, s0, 3
	s_and_b32 s0, s0, -8
	ds_write2_b32 v2, v129, v125 offset0:4 offset1:20
	v_add_u32_e32 v125, 0x4000, v0
	s_sub_i32 s0, s15, s0
	ds_write2_b32 v125, v120, v116 offset0:64 offset1:80
	v_add_u32_e32 v116, 0x4400, v0
	s_lshr_b32 s4, s0, 31
	ds_write2_b32 v116, v121, v117 offset0:68 offset1:84
	v_add_u32_e32 v117, 0x4800, v0
	s_or_b32 s4, s4, 0x1e0
	ds_write2_b32 v117, v122, v118 offset0:72 offset1:88
	v_add_u32_e32 v118, 0x4c00, v0
	s_mul_i32 s0, s4, s0
	ds_write2_b32 v118, v123, v119 offset0:76 offset1:92
	v_add_u32_e32 v119, 0x8000, v0
	s_add_i32 s0, s0, s1
	ds_write2_b32 v119, v112, v108 offset0:128 offset1:144
	v_add_u32_e32 v108, 0x8400, v0
	s_mul_hi_i32 s1, s0, 0x88888889
	ds_write2_b32 v108, v113, v109 offset0:132 offset1:148
	v_add_u32_e32 v109, 0x8800, v0
	s_add_i32 s1, s1, s0
	ds_write2_b32 v109, v114, v110 offset0:136 offset1:152
	v_add_u32_e32 v110, 0x8c00, v0
	s_lshr_b32 s4, s1, 31
	s_ashr_i32 s1, s1, 8
	ds_write2_b32 v110, v115, v111 offset0:140 offset1:156
	v_add_u32_e32 v111, 0xc000, v0
	s_add_i32 s1, s1, s4
	ds_write2_b32 v111, v104, v100 offset0:192 offset1:208
	v_add_u32_e32 v100, 0xc400, v0
	s_lshl_b32 s4, s1, 3
	ds_write2_b32 v100, v105, v101 offset0:196 offset1:212
	v_add_u32_e32 v101, 0xc800, v0
	s_sub_i32 s5, 64, s4
	ds_write2_b32 v0, v128, v124 offset1:16
	v_add_u32_e32 v3, 0x800, v0
	v_add_u32_e32 v124, 0xc00, v0
	ds_write2_b32 v101, v106, v102 offset0:200 offset1:216
	v_add_u32_e32 v102, 0xcc00, v0
	s_min_i32 s5, s5, 8
	ds_write2_b32 v3, v130, v126 offset0:8 offset1:24
	ds_write2_b32 v124, v131, v127 offset0:12 offset1:28
	ds_write2_b32 v102, v107, v103 offset0:204 offset1:220
	ds_write2_b32 v0, v96, v92 offset0:128 offset1:144
	ds_write2_b32 v2, v97, v93 offset0:132 offset1:148
	ds_write2_b32 v3, v98, v94 offset0:136 offset1:152
	ds_write2_b32 v124, v99, v95 offset0:140 offset1:156
	ds_write2_b32 v125, v88, v84 offset0:192 offset1:208
	ds_write2_b32 v116, v89, v85 offset0:196 offset1:212
	ds_write2_b32 v117, v90, v86 offset0:200 offset1:216
	ds_write2_b32 v118, v91, v87 offset0:204 offset1:220
	ds_write2_b32 v108, v80, v76 offset1:16
	ds_write2_b32 v109, v81, v77 offset0:4 offset1:20
	ds_write2_b32 v110, v82, v78 offset0:8 offset1:24
	v_add_u32_e32 v2, 0x9000, v0
	v_add_u32_e32 v0, 0xd000, v0
	s_abs_i32 s6, s5
	ds_write2_b32 v2, v83, v79 offset0:12 offset1:28
	ds_write2_b32 v100, v72, v68 offset0:64 offset1:80
	ds_write2_b32 v101, v73, v69 offset0:68 offset1:84
	ds_write2_b32 v102, v74, v70 offset0:72 offset1:88
	ds_write2_b32 v0, v75, v71 offset0:76 offset1:92
	v_cvt_f32_u32_e32 v0, s6
	s_sub_i32 s8, 0, s6
	s_mulk_i32 s1, 0x1e0
	s_sub_i32 s0, s0, s1
	v_rcp_iflag_f32_e32 v0, v0
	s_abs_i32 s7, s0
	s_xor_b32 s1, s0, s5
	s_ashr_i32 s1, s1, 31
	v_mul_f32_e32 v0, 0x4f7ffffe, v0
	v_cvt_u32_f32_e32 v0, v0
	s_waitcnt lgkmcnt(0)
	s_barrier
	v_readfirstlane_b32 s9, v0
	s_mul_i32 s8, s8, s9
	s_mul_hi_u32 s8, s9, s8
	s_add_i32 s9, s9, s8
	s_mul_hi_u32 s8, s7, s9
	s_mul_i32 s9, s8, s6
	s_sub_i32 s7, s7, s9
	s_add_i32 s9, s8, 1
	s_sub_i32 s10, s7, s6
	s_cmp_ge_u32 s7, s6
	s_cselect_b32 s8, s9, s8
	s_cselect_b32 s7, s10, s7
	s_add_i32 s9, s8, 1
	s_cmp_ge_u32 s7, s6
	s_cselect_b32 s6, s9, s8
	s_xor_b32 s6, s6, s1
	s_sub_i32 s6, s6, s1
	s_mul_i32 s1, s6, s5
	s_sub_i32 s0, s0, s1
	v_mov_b32_e32 v0, v139
	s_add_i32 s8, s0, s4
	s_lshl_b32 s4, s6, 8
	s_ashr_i32 s5, s4, 31
	v_ashrrev_i32_e32 v68, 5, v0
	v_mad_i64_i32 v[2:3], s[6:7], v68, s51, 0
	v_mad_i64_i32 v[2:3], s[6:7], s8, v210, v[2:3]
	s_lshl_b64 s[4:5], s[4:5], 1
	v_and_b32_e32 v0, 31, v0
	s_add_u32 s6, s66, s4
	v_lshl_or_b32 v2, v0, 3, v2
	s_addc_u32 s7, s67, s5
	v_mul_lo_u32 v68, v68, s81
	v_lshlrev_b32_e32 v0, 4, v0
	s_mul_hi_i32 s1, s8, 0x7a0000
	s_mul_i32 s0, s8, 0x7a0000
	v_lshl_add_u64 v[2:3], s[6:7], 0, v[2:3]
	v_add3_u32 v0, v68, v0, 16
	s_mov_b64 s[6:7], 0
	ds_read_b128 v[232:235], v0
	ds_read_b128 v[236:239], v0 offset:512
; __device__ __forceinline__ int ltid() { int t = threadIdx.x; asm volatile("" : "+v"(t)); return t; }
; template <int AI>
; __device__ __forceinline__ void dump_half(const f32x4 (&acc)[2][2][4][2], float* stage) {
;   const int wid = ltid() >> 6, lane = ltid() & 63, wr = wid >> 2, wc = wid & 3, fr = lane & 15, fq = lane >> 4;
; #pragma unroll
;   for (int bj = 0; bj < 2; ++bj)
; #pragma unroll
;     for (int m = 0; m < 4; ++m)
; #pragma unroll
;       for (int n = 0; n < 2; ++n) {
;         const int r0 = wr * 64 + m * 16 + fq * 4, c = bj * 128 + wc * 32 + n * 16 + fr;
; #pragma unroll
;         for (int j = 0; j < 4; ++j) stage[(r0 + j) * SP + c] = acc[AI][bj][m][n][j];
;       }
; }
; __device__ __forceinline__ void emit_rm(const float* stage, u16* dst, long ld, const float* rs) {
;   const int tid = ltid(), c4 = (tid & 31) * 4, rr = tid >> 5;
; #pragma unroll 1
;   for (int ps = 0; ps < 8; ++ps) {
;     const int r = ps * 16 + rr;
;     const float* s = stage + r * SP + c4;
;     const float4 a = *(const float4*)s, b = *(const float4*)(s + 128);
;     const float f = rs ? rs[r] : 1.f;
;     uint2 o0, o1;
;     o0.x = pack2(a.x * f, a.y * f); o0.y = pack2(a.z * f, a.w * f);
;     o1.x = pack2(b.x * f, b.y * f); o1.y = pack2(b.z * f, b.w * f);
;     *(uint2*)(dst + (long)r * ld + c4) = o0;
;     *(uint2*)(dst + (long)r * ld + 128 + c4) = o1;
;   }
; }
; template <int KIND>
; __device__ __forceinline__ void tile_emit(const Ctx& p, int t, int hd, int s, int half, const float* stage) {
;     ...
;   if (KIND == G_IN0) {
;     tile_map(t, 64, 60, pm, pn);
;     emit_rm(stage, (u16*)(ws + OFF_H0) + ((long)pm * 256 + hr) * H0LD + pn * 256, H0LD, nullptr);
.LBB0_371:
	s_mov_b32 s8, 0xfa00000
	v_add_u32_e32 v0, 0x4100, v0
	s_waitcnt lgkmcnt(0)
	v_cvt_pk_bf16_f32 v68, v232, v233
	v_cvt_pk_bf16_f32 v69, v234, v235
	s_waitcnt lgkmcnt(0)
	v_cvt_pk_bf16_f32 v70, v236, v237
	v_lshl_add_u64 v[72:73], v[2:3], 0, s[6:7]
	s_add_u32 s6, s6, 0x7a000
	v_add_co_u32_e32 v72, vcc, s8, v72
	s_addc_u32 s7, s7, 0
	s_nop 0
	v_addc_co_u32_e32 v73, vcc, 0, v73, vcc
	s_cmp_lg_u32 s6, 0x3d0000
	v_cvt_pk_bf16_f32 v71, v238, v239
	ds_read_b128 v[232:235], v0
	ds_read_b128 v[236:239], v0 offset:512
	global_store_dwordx2 v[72:73], v[68:69], off
	global_store_dwordx2 v[72:73], v[70:71], off offset:256
	s_cbranch_scc1 .LBB0_371
	v_mov_b32_e32 v0, v139
	v_mov_b32_e32 v2, v139
	s_waitcnt lgkmcnt(0)
	s_barrier
	s_nop 0
	v_lshrrev_b32_e32 v68, 2, v0
	v_and_b32_e32 v3, 15, v2
	v_and_b32_e32 v68, 0xfffffc0, v68
	v_lshrrev_b32_e32 v2, 2, v2
	v_lshlrev_b32_e32 v0, 1, v0
	v_and_or_b32 v2, v2, 12, v68
	v_and_b32_e32 v0, 0x180, v0
	v_add_u32_e32 v0, 16, v0
	v_lshlrev_b32_e32 v3, 2, v3
	v_mul_lo_u32 v2, v2, s81
	v_add3_u32 v0, v0, v3, v2
	v_add_u32_e32 v2, 0x400, v0
	ds_write2_b32 v2, v65, v61 offset0:4 offset1:20
	v_add_u32_e32 v61, 0x4000, v0
	ds_write2_b32 v61, v56, v52 offset0:64 offset1:80
	v_add_u32_e32 v52, 0x4400, v0
	ds_write2_b32 v52, v57, v53 offset0:68 offset1:84
	v_add_u32_e32 v53, 0x4800, v0
	ds_write2_b32 v53, v58, v54 offset0:72 offset1:88
	v_add_u32_e32 v54, 0x4c00, v0
	ds_write2_b32 v54, v59, v55 offset0:76 offset1:92
	v_add_u32_e32 v55, 0x8000, v0
	ds_write2_b32 v55, v48, v44 offset0:128 offset1:144
	v_add_u32_e32 v44, 0x8400, v0
	ds_write2_b32 v44, v49, v45 offset0:132 offset1:148
	v_add_u32_e32 v45, 0x8800, v0
	ds_write2_b32 v45, v50, v46 offset0:136 offset1:152
	v_add_u32_e32 v46, 0x8c00, v0
	ds_write2_b32 v46, v51, v47 offset0:140 offset1:156
	v_add_u32_e32 v47, 0xc000, v0
	ds_write2_b32 v47, v40, v36 offset0:192 offset1:208
	v_add_u32_e32 v36, 0xc400, v0
	ds_write2_b32 v36, v41, v37 offset0:196 offset1:212
	v_add_u32_e32 v37, 0xc800, v0
	ds_write2_b32 v0, v64, v60 offset1:16
	v_add_u32_e32 v3, 0x800, v0
	v_add_u32_e32 v60, 0xc00, v0
	ds_write2_b32 v37, v42, v38 offset0:200 offset1:216
	v_add_u32_e32 v38, 0xcc00, v0
	ds_write2_b32 v3, v66, v62 offset0:8 offset1:24
	ds_write2_b32 v60, v67, v63 offset0:12 offset1:28
	ds_write2_b32 v38, v43, v39 offset0:204 offset1:220
	ds_write2_b32 v0, v32, v28 offset0:128 offset1:144
	ds_write2_b32 v2, v33, v29 offset0:132 offset1:148
	ds_write2_b32 v3, v34, v30 offset0:136 offset1:152
	ds_write2_b32 v60, v35, v31 offset0:140 offset1:156
	ds_write2_b32 v61, v24, v20 offset0:192 offset1:208
	ds_write2_b32 v52, v25, v21 offset0:196 offset1:212
	ds_write2_b32 v53, v26, v22 offset0:200 offset1:216
	ds_write2_b32 v54, v27, v23 offset0:204 offset1:220
	ds_write2_b32 v44, v16, v12 offset1:16
	ds_write2_b32 v45, v17, v13 offset0:4 offset1:20
	ds_write2_b32 v46, v18, v14 offset0:8 offset1:24
	v_add_u32_e32 v2, 0x9000, v0
	v_add_u32_e32 v0, 0xd000, v0
	ds_write2_b32 v2, v19, v15 offset0:12 offset1:28
	ds_write2_b32 v36, v8, v4 offset0:64 offset1:80
	ds_write2_b32 v37, v9, v5 offset0:68 offset1:84
	ds_write2_b32 v38, v10, v6 offset0:72 offset1:88
	ds_write2_b32 v0, v11, v7 offset0:76 offset1:92
	v_mov_b32_e32 v0, v139
	s_waitcnt lgkmcnt(0)
	s_barrier
	v_mov_b64_e32 v[2:3], s[0:1]
	v_ashrrev_i32_e32 v4, 5, v0
	v_mad_i64_i32 v[2:3], s[0:1], v4, s51, v[2:3]
	v_and_b32_e32 v5, 31, v0
	v_lshlrev_b32_e32 v0, 3, v5
	s_add_u32 s0, s66, s4
	v_lshl_add_u64 v[2:3], v[2:3], 0, v[0:1]
	s_addc_u32 s1, s67, s5
	v_mul_lo_u32 v0, v4, s81
	v_lshlrev_b32_e32 v4, 4, v5
	v_lshl_add_u64 v[2:3], s[0:1], 0, v[2:3]
	v_add3_u32 v0, v0, v4, 16
	s_mov_b64 s[0:1], 0
	ds_read_b128 v[232:235], v0
	ds_read_b128 v[236:239], v0 offset:512
.LBB0_373:
	s_mov_b32 s4, 0xfdd0000
	v_add_u32_e32 v0, 0x4100, v0
	s_waitcnt lgkmcnt(0)
	v_cvt_pk_bf16_f32 v4, v232, v233
	v_cvt_pk_bf16_f32 v5, v234, v235
	v_cvt_pk_bf16_f32 v6, v236, v237
	v_lshl_add_u64 v[8:9], v[2:3], 0, s[0:1]
	s_add_u32 s0, s0, 0x7a000
	v_add_co_u32_e32 v8, vcc, s4, v8
	s_addc_u32 s1, s1, 0
	s_nop 0
	v_addc_co_u32_e32 v9, vcc, 0, v9, vcc
	s_cmp_lg_u32 s0, 0x3d0000
	v_cvt_pk_bf16_f32 v7, v238, v239
	ds_read_b128 v[232:235], v0
	ds_read_b128 v[236:239], v0 offset:512
	global_store_dwordx2 v[8:9], v[4:5], off
	global_store_dwordx2 v[8:9], v[6:7], off offset:256
	s_cbranch_scc1 .LBB0_373
	s_add_i32 s14, s14, 1
	s_mul_i32 s0, s14, s96
	s_add_i32 s15, s0, s63
	s_cmpk_gt_i32 s15, 0xeff
	s_waitcnt lgkmcnt(0)
	s_barrier
	s_cbranch_scc0 .LBB0_362

; __device__ __forceinline__ int ltid() { int t = threadIdx.x; asm volatile("" : "+v"(t)); return t; }
; template <int AI>
; __device__ __forceinline__ void dump_half(const f32x4 (&acc)[2][2][4][2], float* stage) {
;   const int wid = ltid() >> 6, lane = ltid() & 63, wr = wid >> 2, wc = wid & 3, fr = lane & 15, fq = lane >> 4;
; #pragma unroll
;   for (int bj = 0; bj < 2; ++bj)
; #pragma unroll
;     for (int m = 0; m < 4; ++m)
; #pragma unroll
;       for (int n = 0; n < 2; ++n) {
;         const int r0 = wr * 64 + m * 16 + fq * 4, c = bj * 128 + wc * 32 + n * 16 + fr;
; #pragma unroll
;         for (int j = 0; j < 4; ++j) stage[(r0 + j) * SP + c] = acc[AI][bj][m][n][j];
;       }
; }
; __device__ __forceinline__ void emit_rm(const float* stage, u16* dst, long ld, const float* rs) {
;   const int tid = ltid(), c4 = (tid & 31) * 4, rr = tid >> 5;
; #pragma unroll 1
;   for (int ps = 0; ps < 8; ++ps) {
;     const int r = ps * 16 + rr;
;     const float* s = stage + r * SP + c4;
;     const float4 a = *(const float4*)s, b = *(const float4*)(s + 128);
;     const float f = rs ? rs[r] : 1.f;
;     uint2 o0, o1;
;     o0.x = pack2(a.x * f, a.y * f); o0.y = pack2(a.z * f, a.w * f);
;     o1.x = pack2(b.x * f, b.y * f); o1.y = pack2(b.z * f, b.w * f);
;     *(uint2*)(dst + (long)r * ld + c4) = o0;
;     *(uint2*)(dst + (long)r * ld + 128 + c4) = o1;
;   }
; }
; template <int KIND>
; __device__ __forceinline__ void tile_emit(const Ctx& p, int t, int hd, int s, int half, const float* stage) {
;     ...
;   } else if (KIND == G_OUT0 || KIND == G_OUT1) {
;     tile_map(t, 64, 16, pm, pn);
;     u16* yb = (u16*)(ws + (KIND == G_OUT0 ? OFF_Y0 : OFF_Y1));
;     emit_rm(stage, yb + ((long)pm * 256 + hr) * DM + pn * 256, DM, nullptr);
.LBB0_410:
	v_add_u32_e32 v72, s6, v0
	ds_read_b128 v[68:71], v72
	ds_read_b128 v[72:75], v72 offset:512
	s_addk_i32 s6, 0x4100
	s_cmp_lg_u32 s6, 0x20800
	s_waitcnt lgkmcnt(0)
	v_cvt_pk_bf16_f32 v68, v68, v69
	v_cvt_pk_bf16_f32 v69, v70, v71
	s_waitcnt lgkmcnt(0)
	v_cvt_pk_bf16_f32 v70, v72, v73
	v_cvt_pk_bf16_f32 v71, v74, v75
	global_store_dwordx2 v[2:3], v[68:69], off
	global_store_dwordx2 v[2:3], v[70:71], off offset:256
	v_lshl_add_u64 v[2:3], v[2:3], 0, s[88:89]
	s_cbranch_scc1 .LBB0_410
	v_mov_b32_e32 v0, v139
	v_mov_b32_e32 v2, v139
	s_waitcnt lgkmcnt(0)
	s_barrier
	s_nop 0
	v_lshrrev_b32_e32 v68, 2, v0
	v_and_b32_e32 v3, 15, v2
	v_and_b32_e32 v68, 0xfffffc0, v68
	v_lshrrev_b32_e32 v2, 2, v2
	v_lshlrev_b32_e32 v0, 1, v0
	v_and_or_b32 v2, v2, 12, v68
	v_and_b32_e32 v0, 0x180, v0
	v_add_u32_e32 v0, 16, v0
	v_lshlrev_b32_e32 v3, 2, v3
	v_mul_lo_u32 v2, v2, s81
	v_add3_u32 v0, v0, v3, v2
	v_add_u32_e32 v2, 0x400, v0
	ds_write2_b32 v2, v65, v61 offset0:4 offset1:20
	v_add_u32_e32 v61, 0x4000, v0
	ds_write2_b32 v61, v56, v52 offset0:64 offset1:80
	v_add_u32_e32 v52, 0x4400, v0
	ds_write2_b32 v52, v57, v53 offset0:68 offset1:84
	v_add_u32_e32 v53, 0x4800, v0
	ds_write2_b32 v53, v58, v54 offset0:72 offset1:88
	v_add_u32_e32 v54, 0x4c00, v0
	ds_write2_b32 v54, v59, v55 offset0:76 offset1:92
	v_add_u32_e32 v55, 0x8000, v0
	ds_write2_b32 v55, v48, v44 offset0:128 offset1:144
	v_add_u32_e32 v44, 0x8400, v0
	ds_write2_b32 v44, v49, v45 offset0:132 offset1:148
	v_add_u32_e32 v45, 0x8800, v0
	ds_write2_b32 v45, v50, v46 offset0:136 offset1:152
	v_add_u32_e32 v46, 0x8c00, v0
	ds_write2_b32 v46, v51, v47 offset0:140 offset1:156
	v_add_u32_e32 v47, 0xc000, v0
	ds_write2_b32 v47, v40, v36 offset0:192 offset1:208
	v_add_u32_e32 v36, 0xc400, v0
	ds_write2_b32 v36, v41, v37 offset0:196 offset1:212
	v_add_u32_e32 v37, 0xc800, v0
	ds_write2_b32 v0, v64, v60 offset1:16
	v_add_u32_e32 v3, 0x800, v0
	v_add_u32_e32 v60, 0xc00, v0
	ds_write2_b32 v37, v42, v38 offset0:200 offset1:216
	v_add_u32_e32 v38, 0xcc00, v0
	ds_write2_b32 v3, v66, v62 offset0:8 offset1:24
	ds_write2_b32 v60, v67, v63 offset0:12 offset1:28
	ds_write2_b32 v38, v43, v39 offset0:204 offset1:220
	ds_write2_b32 v0, v32, v28 offset0:128 offset1:144
	ds_write2_b32 v2, v33, v29 offset0:132 offset1:148
	ds_write2_b32 v3, v34, v30 offset0:136 offset1:152
	ds_write2_b32 v60, v35, v31 offset0:140 offset1:156
	ds_write2_b32 v61, v24, v20 offset0:192 offset1:208
	ds_write2_b32 v52, v25, v21 offset0:196 offset1:212
	ds_write2_b32 v53, v26, v22 offset0:200 offset1:216
	ds_write2_b32 v54, v27, v23 offset0:204 offset1:220
	ds_write2_b32 v44, v16, v12 offset1:16
	ds_write2_b32 v45, v17, v13 offset0:4 offset1:20
	ds_write2_b32 v46, v18, v14 offset0:8 offset1:24
	v_add_u32_e32 v2, 0x9000, v0
	v_add_u32_e32 v0, 0xd000, v0
	ds_write2_b32 v2, v19, v15 offset0:12 offset1:28
	ds_write2_b32 v36, v8, v4 offset0:64 offset1:80
	ds_write2_b32 v37, v9, v5 offset0:68 offset1:84
	ds_write2_b32 v38, v10, v6 offset0:72 offset1:88
	ds_write2_b32 v0, v11, v7 offset0:76 offset1:92
	v_mov_b32_e32 v0, v139
	s_waitcnt lgkmcnt(0)
	s_barrier
	s_nop 0
	v_ashrrev_i32_e32 v4, 5, v0
	v_ashrrev_i32_e32 v5, 31, v4
	v_lshlrev_b64 v[2:3], 13, v[4:5]
	v_and_b32_e32 v5, 31, v0
	v_lshl_add_u64 v[2:3], s[0:1], 0, v[2:3]
	v_lshlrev_b32_e32 v0, 3, v5
	s_add_u32 s0, s66, s4
	v_lshl_add_u64 v[2:3], v[2:3], 0, v[0:1]
	s_addc_u32 s1, s67, s5
	v_mul_lo_u32 v0, v4, s81
	v_lshlrev_b32_e32 v4, 4, v5
	v_lshl_add_u64 v[2:3], s[0:1], 0, v[2:3]
	v_add3_u32 v0, v0, v4, 16
	s_mov_b64 s[0:1], 0
	ds_read_b128 v[232:235], v0
	ds_read_b128 v[236:239], v0 offset:512
.LBB0_412:
	v_add_u32_e32 v0, 0x4100, v0
	s_waitcnt lgkmcnt(0)
	v_cvt_pk_bf16_f32 v4, v232, v233
	v_cvt_pk_bf16_f32 v5, v234, v235
	v_cvt_pk_bf16_f32 v6, v236, v237
	v_lshl_add_u64 v[8:9], v[2:3], 0, s[0:1]
	s_add_u32 s0, s0, 0x20000
	v_add_co_u32_e32 v8, vcc, s69, v8
	s_addc_u32 s1, s1, 0
	s_nop 0
	v_addc_co_u32_e32 v9, vcc, 0, v9, vcc
	s_cmp_lg_u32 s0, 0x100000
	v_cvt_pk_bf16_f32 v7, v238, v239
	ds_read_b128 v[232:235], v0
	ds_read_b128 v[236:239], v0 offset:512
	global_store_dwordx2 v[8:9], v[4:5], off
	global_store_dwordx2 v[8:9], v[6:7], off offset:256
	s_cbranch_scc1 .LBB0_412
	s_add_i32 s13, s13, 1
	s_mul_i32 s0, s13, s96
	s_add_i32 s14, s0, s63
	s_cmpk_gt_i32 s14, 0x3ff
	s_waitcnt lgkmcnt(0)
	s_barrier
	s_cbranch_scc0 .LBB0_401

; __device__ __forceinline__ int ltid() { int t = threadIdx.x; asm volatile("" : "+v"(t)); return t; }
; __device__ __forceinline__ void emit_rm(const float* stage, u16* dst, long ld, const float* rs) {
;   const int tid = ltid(), c4 = (tid & 31) * 4, rr = tid >> 5;
; #pragma unroll 1
;   for (int ps = 0; ps < 8; ++ps) {
;     const int r = ps * 16 + rr;
;     const float* s = stage + r * SP + c4;
;     const float4 a = *(const float4*)s, b = *(const float4*)(s + 128);
;     const float f = rs ? rs[r] : 1.f;
;     uint2 o0, o1;
;     o0.x = pack2(a.x * f, a.y * f); o0.y = pack2(a.z * f, a.w * f);
;     o1.x = pack2(b.x * f, b.y * f); o1.y = pack2(b.z * f, b.w * f);
;     *(uint2*)(dst + (long)r * ld + c4) = o0;
;     *(uint2*)(dst + (long)r * ld + 128 + c4) = o1;
;   }
; }
; template <int KIND>
; __device__ __forceinline__ void tile_emit(const Ctx& p, int t, int hd, int s, int half, const float* stage) {
;     ...
;   } else {
;     int tb, tc, tr, tv; num_decode(t, tb, tc, tr, tv);
;     emit_rm(stage, (u16*)(ws + OFF_KH) + ((long)tb * SEQ + tc * 2048 + tr * 256 + hr) * LDQ + tv * 256, LDQ,
;             (const float*)(ws + OFF_RDEN) + tb * SEQ + tc * 2048 + tr * 256 + hr);
.LBB0_465:
	s_lshl_b32 s11, s8, 13
	s_lshl_b32 s12, s9, 8
	s_and_b32 s11, s11, 0x2000
	s_ashr_i32 s13, s12, 31
	s_add_u32 s9, s4, s12
	s_addc_u32 s29, s5, s13
	s_add_u32 s9, s9, s11
	s_addc_u32 s11, s29, 0
	s_mulk_i32 s11, 0x1080
	s_mul_hi_u32 s29, s9, 0x1080
	s_and_b32 s10, s10, 7
	s_add_i32 s29, s29, s11
	s_mulk_i32 s9, 0x1080
	s_lshl_b32 s10, s10, 9
	s_add_u32 s10, s10, s9
	s_addc_u32 s11, 0, s29
	s_and_b32 s8, s8, 1
	v_mov_b32_e32 v0, v139
	s_lshl_b32 s8, s8, 15
	s_lshl_b64 s[4:5], s[4:5], 2
	v_mov_b64_e32 v[2:3], s[10:11]
	v_ashrrev_i32_e32 v68, 5, v0
	s_movk_i32 s9, 0x1080
	s_add_u32 s8, s8, s4
	v_mad_i64_i32 v[2:3], s[10:11], v68, s9, v[2:3]
	s_addc_u32 s9, 0, s5
	s_lshl_b64 s[4:5], s[12:13], 2
	s_add_u32 s4, s8, s4
	v_and_b32_e32 v70, 31, v0
	s_addc_u32 s5, s9, s5
	v_lshlrev_b32_e32 v0, 3, v70
	s_add_u32 s4, s4, 0x43740000
	v_ashrrev_i32_e32 v69, 31, v68
	v_lshl_add_u64 v[2:3], v[2:3], 0, v[0:1]
	v_mul_lo_u32 v0, v68, s81
	v_lshlrev_b32_e32 v70, 4, v70
	s_addc_u32 s5, s5, 0
	v_add3_u32 v0, v0, v70, 16
	v_lshl_add_u64 v[68:69], v[68:69], 2, s[4:5]
	s_mov_b32 s4, 0
	s_mov_b64 s[8:9], 0x10800
	v_lshl_add_u64 v[70:71], s[66:67], 0, v[68:69]
	global_load_dword v172, v[70:71], off
	v_lshl_add_u64 v[68:69], v[68:69], 0, 64
	v_add_u32_e32 v75, s4, v0
	ds_read_b128 v[164:167], v75
	ds_read_b128 v[168:171], v75 offset:512
	s_waitcnt vmcnt(0)
.LBB0_466:
	s_addk_i32 s4, 0x4100
	s_waitcnt vmcnt(2) lgkmcnt(0)
	v_mov_b32_e32 v74, v172
	s_nop 0
	v_pk_mul_f32 v[70:71], v[164:165], v[74:75] op_sel_hi:[1,0]
	s_nop 0
	v_cvt_pk_bf16_f32 v76, v70, v71
	v_pk_mul_f32 v[70:71], v[166:167], v[74:75] op_sel_hi:[1,0]
	s_nop 0
	v_cvt_pk_bf16_f32 v77, v70, v71
	v_pk_mul_f32 v[70:71], v[168:169], v[74:75] op_sel_hi:[1,0]
	v_pk_mul_f32 v[72:73], v[170:171], v[74:75] op_sel_hi:[1,0]
	v_cvt_pk_bf16_f32 v70, v70, v71
	v_cvt_pk_bf16_f32 v71, v72, v73
	v_lshl_add_u64 v[174:175], s[66:67], 0, v[68:69]
	global_load_dword v172, v[174:175], off
	v_lshl_add_u64 v[68:69], v[68:69], 0, 64
	v_add_u32_e32 v75, s4, v0
	ds_read_b128 v[164:167], v75
	ds_read_b128 v[168:171], v75 offset:512
	v_lshl_add_u64 v[72:73], s[66:67], 0, v[2:3]
	v_add_co_u32_e32 v72, vcc, 0x4200000, v72
	v_lshl_add_u64 v[2:3], v[2:3], 0, s[8:9]
	s_nop 0
	v_addc_co_u32_e32 v73, vcc, 0, v73, vcc
	global_store_dwordx2 v[72:73], v[76:77], off
	global_store_dwordx2 v[72:73], v[70:71], off offset:256
	s_cmp_lg_u32 s4, 0x20800
	s_cbranch_scc1 .LBB0_466
	v_mov_b32_e32 v0, v139
	v_mov_b32_e32 v2, v139
	s_waitcnt lgkmcnt(0)
	s_barrier
	s_mov_b64 s[4:5], -1
	v_lshrrev_b32_e32 v68, 2, v0
	v_and_b32_e32 v3, 15, v2
	v_and_b32_e32 v68, 0xfffffc0, v68
	v_lshrrev_b32_e32 v2, 2, v2
	v_lshlrev_b32_e32 v0, 1, v0
	v_and_or_b32 v2, v2, 12, v68
	v_and_b32_e32 v0, 0x180, v0
	v_add_u32_e32 v0, 16, v0
	v_lshlrev_b32_e32 v3, 2, v3
	v_mul_lo_u32 v2, v2, s81
	v_add3_u32 v0, v0, v3, v2
	v_add_u32_e32 v2, 0x400, v0
	ds_write2_b32 v2, v65, v61 offset0:4 offset1:20
	v_add_u32_e32 v61, 0x4000, v0
	ds_write2_b32 v61, v56, v52 offset0:64 offset1:80
	v_add_u32_e32 v52, 0x4400, v0
	ds_write2_b32 v52, v57, v53 offset0:68 offset1:84
	v_add_u32_e32 v53, 0x4800, v0
	ds_write2_b32 v53, v58, v54 offset0:72 offset1:88
	v_add_u32_e32 v54, 0x4c00, v0
	ds_write2_b32 v54, v59, v55 offset0:76 offset1:92
	v_add_u32_e32 v55, 0x8000, v0
	ds_write2_b32 v55, v48, v44 offset0:128 offset1:144
	v_add_u32_e32 v44, 0x8400, v0
	ds_write2_b32 v44, v49, v45 offset0:132 offset1:148
	v_add_u32_e32 v45, 0x8800, v0
	ds_write2_b32 v45, v50, v46 offset0:136 offset1:152
	v_add_u32_e32 v46, 0x8c00, v0
	ds_write2_b32 v46, v51, v47 offset0:140 offset1:156
	v_add_u32_e32 v47, 0xc000, v0
	ds_write2_b32 v47, v40, v36 offset0:192 offset1:208
	v_add_u32_e32 v36, 0xc400, v0
	ds_write2_b32 v36, v41, v37 offset0:196 offset1:212
	v_add_u32_e32 v37, 0xc800, v0
	ds_write2_b32 v0, v64, v60 offset1:16
	v_add_u32_e32 v3, 0x800, v0
	v_add_u32_e32 v60, 0xc00, v0
	ds_write2_b32 v37, v42, v38 offset0:200 offset1:216
	v_add_u32_e32 v38, 0xcc00, v0
	ds_write2_b32 v3, v66, v62 offset0:8 offset1:24
	ds_write2_b32 v60, v67, v63 offset0:12 offset1:28
	ds_write2_b32 v38, v43, v39 offset0:204 offset1:220
	ds_write2_b32 v0, v32, v28 offset0:128 offset1:144
	ds_write2_b32 v2, v33, v29 offset0:132 offset1:148
	ds_write2_b32 v3, v34, v30 offset0:136 offset1:152
	ds_write2_b32 v60, v35, v31 offset0:140 offset1:156
	ds_write2_b32 v61, v24, v20 offset0:192 offset1:208
	ds_write2_b32 v52, v25, v21 offset0:196 offset1:212
	ds_write2_b32 v53, v26, v22 offset0:200 offset1:216
	ds_write2_b32 v54, v27, v23 offset0:204 offset1:220
	ds_write2_b32 v44, v16, v12 offset1:16
	ds_write2_b32 v45, v17, v13 offset0:4 offset1:20
	ds_write2_b32 v46, v18, v14 offset0:8 offset1:24
	v_add_u32_e32 v2, 0x9000, v0
	v_add_u32_e32 v0, 0xd000, v0
	s_and_b64 vcc, exec, s[0:1]
	ds_write2_b32 v2, v19, v15 offset0:12 offset1:28
	ds_write2_b32 v36, v8, v4 offset0:64 offset1:80
	ds_write2_b32 v37, v9, v5 offset0:68 offset1:84
	ds_write2_b32 v38, v10, v6 offset0:72 offset1:88
	ds_write2_b32 v0, v11, v7 offset0:76 offset1:92
	s_waitcnt lgkmcnt(0)
	s_barrier
	s_cbranch_vccz .LBB0_469
	s_add_i32 s0, s28, 0xfffffe80
	s_lshr_b32 s0, s0, 4
	s_sub_i32 s8, 7, s0
	s_lshr_b32 s9, s28, 3
	s_mov_b64 s[4:5], 0

; __device__ __forceinline__ int ltid() { int t = threadIdx.x; asm volatile("" : "+v"(t)); return t; }
; __device__ __forceinline__ void emit_rm(const float* stage, u16* dst, long ld, const float* rs) {
;   const int tid = ltid(), c4 = (tid & 31) * 4, rr = tid >> 5;
; #pragma unroll 1
;   for (int ps = 0; ps < 8; ++ps) {
;     const int r = ps * 16 + rr;
;     const float* s = stage + r * SP + c4;
;     const float4 a = *(const float4*)s, b = *(const float4*)(s + 128);
;     const float f = rs ? rs[r] : 1.f;
;     uint2 o0, o1;
;     o0.x = pack2(a.x * f, a.y * f); o0.y = pack2(a.z * f, a.w * f);
;     o1.x = pack2(b.x * f, b.y * f); o1.y = pack2(b.z * f, b.w * f);
;     *(uint2*)(dst + (long)r * ld + c4) = o0;
;     *(uint2*)(dst + (long)r * ld + 128 + c4) = o1;
;   }
; }
; template <int KIND>
; __device__ __forceinline__ void tile_emit(const Ctx& p, int t, int hd, int s, int half, const float* stage) {
;     ...
;   } else {
;     int tb, tc, tr, tv; num_decode(t, tb, tc, tr, tv);
;     emit_rm(stage, (u16*)(ws + OFF_KH) + ((long)tb * SEQ + tc * 2048 + tr * 256 + hr) * LDQ + tv * 256, LDQ,
;             (const float*)(ws + OFF_RDEN) + tb * SEQ + tc * 2048 + tr * 256 + hr);
.LBB0_471:
	s_lshl_b32 s4, s8, 8
	s_ashr_i32 s5, s4, 31
	s_and_b32 s8, s9, 1
	s_add_u32 s7, s0, s4
	s_addc_u32 s9, s1, s5
	s_mulk_i32 s9, 0x1080
	s_mul_hi_u32 s10, s7, 0x1080
	s_mul_i32 s6, s8, 0x2100000
	s_add_i32 s10, s10, s9
	s_mulk_i32 s7, 0x1080
	s_add_u32 s6, s6, s7
	s_addc_u32 s7, 0, s10
	s_and_b32 s9, s28, 7
	s_lshl_b32 s9, s9, 9
	s_add_u32 s6, s9, s6
	v_mov_b32_e32 v0, v139
	s_addc_u32 s7, 0, s7
	v_mov_b64_e32 v[2:3], s[6:7]
	v_ashrrev_i32_e32 v4, 5, v0
	s_movk_i32 s6, 0x1080
	v_mad_i64_i32 v[2:3], s[6:7], v4, s6, v[2:3]
	s_lshl_b32 s6, s8, 15
	s_lshl_b64 s[0:1], s[0:1], 2
	s_add_u32 s6, s6, s0
	s_addc_u32 s7, 0, s1
	s_lshl_b64 s[0:1], s[4:5], 2
	s_add_u32 s0, s6, s0
	v_and_b32_e32 v6, 31, v0
	s_addc_u32 s1, s7, s1
	v_lshlrev_b32_e32 v0, 3, v6
	s_add_u32 s0, s0, 0x43740200
	v_ashrrev_i32_e32 v5, 31, v4
	v_lshl_add_u64 v[2:3], v[2:3], 0, v[0:1]
	v_mul_lo_u32 v0, v4, s81
	v_lshlrev_b32_e32 v6, 4, v6
	s_addc_u32 s1, s1, 0
	v_add3_u32 v0, v0, v6, 16
	v_lshl_add_u64 v[4:5], v[4:5], 2, s[0:1]
	s_mov_b32 s0, 0
	s_mov_b64 s[4:5], 0x10800
	v_lshl_add_u64 v[6:7], s[66:67], 0, v[4:5]
	global_load_dword v172, v[6:7], off
	v_lshl_add_u64 v[4:5], v[4:5], 0, 64
	v_add_u32_e32 v11, s0, v0
	ds_read_b128 v[164:167], v11
	ds_read_b128 v[168:171], v11 offset:512
	s_waitcnt vmcnt(0)
.LBB0_472:
	s_addk_i32 s0, 0x4100
	s_waitcnt vmcnt(2) lgkmcnt(0)
	v_mov_b32_e32 v10, v172
	s_nop 0
	v_pk_mul_f32 v[6:7], v[164:165], v[10:11] op_sel_hi:[1,0]
	s_nop 0
	v_cvt_pk_bf16_f32 v12, v6, v7
	v_pk_mul_f32 v[6:7], v[166:167], v[10:11] op_sel_hi:[1,0]
	s_nop 0
	v_cvt_pk_bf16_f32 v13, v6, v7
	v_pk_mul_f32 v[6:7], v[168:169], v[10:11] op_sel_hi:[1,0]
	v_pk_mul_f32 v[8:9], v[170:171], v[10:11] op_sel_hi:[1,0]
	v_cvt_pk_bf16_f32 v6, v6, v7
	v_cvt_pk_bf16_f32 v7, v8, v9
	v_lshl_add_u64 v[174:175], s[66:67], 0, v[4:5]
	global_load_dword v172, v[174:175], off
	v_lshl_add_u64 v[4:5], v[4:5], 0, 64
	v_add_u32_e32 v11, s0, v0
	ds_read_b128 v[164:167], v11
	ds_read_b128 v[168:171], v11 offset:512
	v_lshl_add_u64 v[8:9], s[66:67], 0, v[2:3]
	v_add_co_u32_e32 v8, vcc, 0x4284000, v8
	v_lshl_add_u64 v[2:3], v[2:3], 0, s[4:5]
	s_nop 0
	v_addc_co_u32_e32 v9, vcc, 0, v9, vcc
	global_store_dwordx2 v[8:9], v[12:13], off
	global_store_dwordx2 v[8:9], v[6:7], off offset:256
	s_cmp_lg_u32 s0, 0x20800
	s_cbranch_scc1 .LBB0_472
	s_add_i32 s27, s27, 1
	s_mov_b64 s[4:5], 0
	s_waitcnt lgkmcnt(0)
	s_barrier
	s_branch .LBB0_426

; __device__ __forceinline__ int ltid() { int t = threadIdx.x; asm volatile("" : "+v"(t)); return t; }
; template <int AI>
; __device__ __forceinline__ void dump_half(const f32x4 (&acc)[2][2][4][2], float* stage) {
;   const int wid = ltid() >> 6, lane = ltid() & 63, wr = wid >> 2, wc = wid & 3, fr = lane & 15, fq = lane >> 4;
; #pragma unroll
;   for (int bj = 0; bj < 2; ++bj)
; #pragma unroll
;     for (int m = 0; m < 4; ++m)
; #pragma unroll
;       for (int n = 0; n < 2; ++n) {
;         const int r0 = wr * 64 + m * 16 + fq * 4, c = bj * 128 + wc * 32 + n * 16 + fr;
; #pragma unroll
;         for (int j = 0; j < 4; ++j) stage[(r0 + j) * SP + c] = acc[AI][bj][m][n][j];
;       }
; }
; __device__ __forceinline__ void emit_rm(const float* stage, u16* dst, long ld, const float* rs) {
;   const int tid = ltid(), c4 = (tid & 31) * 4, rr = tid >> 5;
; #pragma unroll 1
;   for (int ps = 0; ps < 8; ++ps) {
;     const int r = ps * 16 + rr;
;     const float* s = stage + r * SP + c4;
;     const float4 a = *(const float4*)s, b = *(const float4*)(s + 128);
;     const float f = rs ? rs[r] : 1.f;
;     uint2 o0, o1;
;     o0.x = pack2(a.x * f, a.y * f); o0.y = pack2(a.z * f, a.w * f);
;     o1.x = pack2(b.x * f, b.y * f); o1.y = pack2(b.z * f, b.w * f);
;     *(uint2*)(dst + (long)r * ld + c4) = o0;
;     *(uint2*)(dst + (long)r * ld + 128 + c4) = o1;
;   }
; }
; template <int KIND>
; __device__ __forceinline__ void tile_emit(const Ctx& p, int t, int hd, int s, int half, const float* stage) {
;     ...
;   } else if (KIND == G_G) {
;     int tb = t >> 6, tv = (t & 63) >> 3, tj = t & 7;
;     emit_rm(stage, (u16*)(ws + OFF_GTH) + (((long)tb * 3 + s) * 2048 + tv * 256 + hr) * 2048 + tj * 256, 2048, nullptr);
.LBB0_504:
	s_or_b64 exec, exec, s[4:5]
	v_mov_b32_e32 v0, v139
	v_mov_b32_e32 v2, v139
	s_barrier
	s_ashr_i32 s1, s28, 6
	v_lshrrev_b32_e32 v132, 2, v0
	v_and_b32_e32 v3, 15, v2
	v_and_b32_e32 v132, 0xfffffc0, v132
	v_lshrrev_b32_e32 v2, 2, v2
	v_lshlrev_b32_e32 v0, 1, v0
	v_and_or_b32 v2, v2, 12, v132
	v_and_b32_e32 v0, 0x180, v0
	v_add_u32_e32 v0, 16, v0
	v_lshlrev_b32_e32 v3, 2, v3
	v_mul_lo_u32 v2, v2, s81
	v_add3_u32 v0, v0, v3, v2
	v_add_u32_e32 v141, 0x8000, v0
	v_add_u32_e32 v144, 0xc000, v0
	v_add_u32_e32 v2, 0x400, v0
	v_add_u32_e32 v3, 0x800, v0
	v_add_u32_e32 v132, 0xc00, v0
	v_add_u32_e32 v133, 0x4000, v0
	v_add_u32_e32 v134, 0x4400, v0
	v_add_u32_e32 v135, 0x4800, v0
	v_add_u32_e32 v136, 0x4c00, v0
	ds_write2_b32 v141, v112, v108 offset0:128 offset1:144
	v_add_u32_e32 v141, 0x8400, v0
	v_add_u32_e32 v142, 0x8800, v0
	v_add_u32_e32 v143, 0x8c00, v0
	ds_write2_b32 v144, v104, v100 offset0:192 offset1:208
	v_add_u32_e32 v144, 0xc400, v0
	v_add_u32_e32 v145, 0xc800, v0
	v_add_u32_e32 v146, 0xcc00, v0
	s_mul_i32 s1, s1, 3
	ds_write2_b32 v0, v128, v124 offset1:16
	ds_write2_b32 v2, v129, v125 offset0:4 offset1:20
	ds_write2_b32 v3, v130, v126 offset0:8 offset1:24
	ds_write2_b32 v132, v131, v127 offset0:12 offset1:28
	ds_write2_b32 v133, v120, v116 offset0:64 offset1:80
	ds_write2_b32 v134, v121, v117 offset0:68 offset1:84
	ds_write2_b32 v135, v122, v118 offset0:72 offset1:88
	ds_write2_b32 v136, v123, v119 offset0:76 offset1:92
	ds_write2_b32 v141, v113, v109 offset0:132 offset1:148
	ds_write2_b32 v142, v114, v110 offset0:136 offset1:152
	ds_write2_b32 v143, v115, v111 offset0:140 offset1:156
	ds_write2_b32 v144, v105, v101 offset0:196 offset1:212
	ds_write2_b32 v145, v106, v102 offset0:200 offset1:216
	ds_write2_b32 v146, v107, v103 offset0:204 offset1:220
	ds_write2_b32 v0, v96, v92 offset0:128 offset1:144
	ds_write2_b32 v2, v97, v93 offset0:132 offset1:148
	ds_write2_b32 v3, v98, v94 offset0:136 offset1:152
	ds_write2_b32 v132, v99, v95 offset0:140 offset1:156
	ds_write2_b32 v133, v88, v84 offset0:192 offset1:208
	ds_write2_b32 v134, v89, v85 offset0:196 offset1:212
	ds_write2_b32 v135, v90, v86 offset0:200 offset1:216
	ds_write2_b32 v136, v91, v87 offset0:204 offset1:220
	ds_write2_b32 v141, v80, v76 offset1:16
	ds_write2_b32 v142, v81, v77 offset0:4 offset1:20
	ds_write2_b32 v143, v82, v78 offset0:8 offset1:24
	v_add_u32_e32 v2, 0x9000, v0
	v_add_u32_e32 v0, 0xd000, v0
	s_ashr_i32 s5, s1, 31
	s_ashr_i32 s6, s0, 31
	ds_write2_b32 v2, v83, v79 offset0:12 offset1:28
	ds_write2_b32 v144, v72, v68 offset0:64 offset1:80
	ds_write2_b32 v145, v73, v69 offset0:68 offset1:84
	ds_write2_b32 v146, v74, v70 offset0:72 offset1:88
	ds_write2_b32 v0, v75, v71 offset0:76 offset1:92
	s_add_u32 s4, s1, s0
	v_mov_b32_e32 v0, v139
	s_waitcnt lgkmcnt(0)
	s_barrier
	s_addc_u32 s5, s5, s6
	s_lshl_b32 s1, s28, 17
	s_and_b32 s1, s1, 0x700000
	v_ashrrev_i32_e32 v132, 5, v0
	s_lshl_b64 s[4:5], s[4:5], 23
	v_ashrrev_i32_e32 v133, 31, v132
	s_or_b32 s4, s4, s1
	v_lshlrev_b64 v[2:3], 12, v[132:133]
	s_lshl_b32 s1, s28, 9
	v_and_b32_e32 v0, 31, v0
	v_lshl_add_u64 v[2:3], s[4:5], 0, v[2:3]
	s_and_b32 s1, s1, 0xe00
	v_lshlrev_b32_e32 v133, 3, v0
	v_or3_b32 v2, v2, s1, v133
	v_mul_lo_u32 v132, v132, s81
	v_lshlrev_b32_e32 v0, 4, v0
	v_lshl_add_u64 v[2:3], s[66:67], 0, v[2:3]
	v_add3_u32 v0, v132, v0, 16
	s_mov_b64 s[6:7], 0
	ds_read_b128 v[232:235], v0
	ds_read_b128 v[236:239], v0 offset:512
; __device__ __forceinline__ int ltid() { int t = threadIdx.x; asm volatile("" : "+v"(t)); return t; }
; template <int AI>
; __device__ __forceinline__ void dump_half(const f32x4 (&acc)[2][2][4][2], float* stage) {
;   const int wid = ltid() >> 6, lane = ltid() & 63, wr = wid >> 2, wc = wid & 3, fr = lane & 15, fq = lane >> 4;
; #pragma unroll
;   for (int bj = 0; bj < 2; ++bj)
; #pragma unroll
;     for (int m = 0; m < 4; ++m)
; #pragma unroll
;       for (int n = 0; n < 2; ++n) {
;         const int r0 = wr * 64 + m * 16 + fq * 4, c = bj * 128 + wc * 32 + n * 16 + fr;
; #pragma unroll
;         for (int j = 0; j < 4; ++j) stage[(r0 + j) * SP + c] = acc[AI][bj][m][n][j];
;       }
; }
; __device__ __forceinline__ void emit_rm(const float* stage, u16* dst, long ld, const float* rs) {
;   const int tid = ltid(), c4 = (tid & 31) * 4, rr = tid >> 5;
; #pragma unroll 1
;   for (int ps = 0; ps < 8; ++ps) {
;     const int r = ps * 16 + rr;
;     const float* s = stage + r * SP + c4;
;     const float4 a = *(const float4*)s, b = *(const float4*)(s + 128);
;     const float f = rs ? rs[r] : 1.f;
;     uint2 o0, o1;
;     o0.x = pack2(a.x * f, a.y * f); o0.y = pack2(a.z * f, a.w * f);
;     o1.x = pack2(b.x * f, b.y * f); o1.y = pack2(b.z * f, b.w * f);
;     *(uint2*)(dst + (long)r * ld + c4) = o0;
;     *(uint2*)(dst + (long)r * ld + 128 + c4) = o1;
;   }
; }
; template <int KIND>
; __device__ __forceinline__ void tile_emit(const Ctx& p, int t, int hd, int s, int half, const float* stage) {
;     ...
;   } else if (KIND == G_G) {
;     int tb = t >> 6, tv = (t & 63) >> 3, tj = t & 7;
;     emit_rm(stage, (u16*)(ws + OFF_GTH) + (((long)tb * 3 + s) * 2048 + tv * 256 + hr) * 2048 + tj * 256, 2048, nullptr);
.LBB0_505:
	v_add_u32_e32 v0, 0x4100, v0
	s_waitcnt lgkmcnt(0)
	v_cvt_pk_bf16_f32 v132, v232, v233
	v_cvt_pk_bf16_f32 v133, v234, v235
	s_waitcnt lgkmcnt(0)
	v_cvt_pk_bf16_f32 v134, v236, v237
	v_lshl_add_u64 v[142:143], v[2:3], 0, s[6:7]
	s_add_u32 s6, s6, 0x10000
	v_add_co_u32_e32 v142, vcc, s80, v142
	s_addc_u32 s7, s7, 0
	s_nop 0
	v_addc_co_u32_e32 v143, vcc, 0, v143, vcc
	s_cmp_lg_u32 s6, 0x80000
	v_cvt_pk_bf16_f32 v135, v238, v239
	ds_read_b128 v[232:235], v0
	ds_read_b128 v[236:239], v0 offset:512
	global_store_dwordx2 v[142:143], v[132:133], off
	global_store_dwordx2 v[142:143], v[134:135], off offset:256
	s_cbranch_scc1 .LBB0_505
	v_mov_b32_e32 v0, v139
	v_mov_b32_e32 v2, v139
	s_waitcnt lgkmcnt(0)
	s_barrier
	s_add_u32 s4, s1, s4
	v_lshrrev_b32_e32 v132, 2, v0
	v_and_b32_e32 v3, 15, v2
	v_and_b32_e32 v132, 0xfffffc0, v132
	v_lshrrev_b32_e32 v2, 2, v2
	v_lshlrev_b32_e32 v0, 1, v0
	v_and_or_b32 v2, v2, 12, v132
	v_and_b32_e32 v0, 0x180, v0
	v_add_u32_e32 v0, 16, v0
	v_lshlrev_b32_e32 v3, 2, v3
	v_mul_lo_u32 v2, v2, s81
	v_add3_u32 v0, v0, v3, v2
	v_add_u32_e32 v141, 0x8000, v0
	v_add_u32_e32 v144, 0xc000, v0
	v_add_u32_e32 v2, 0x400, v0
	v_add_u32_e32 v3, 0x800, v0
	v_add_u32_e32 v132, 0xc00, v0
	v_add_u32_e32 v133, 0x4000, v0
	v_add_u32_e32 v134, 0x4400, v0
	v_add_u32_e32 v135, 0x4800, v0
	v_add_u32_e32 v136, 0x4c00, v0
	ds_write2_b32 v141, v48, v44 offset0:128 offset1:144
	v_add_u32_e32 v141, 0x8400, v0
	v_add_u32_e32 v142, 0x8800, v0
	v_add_u32_e32 v143, 0x8c00, v0
	ds_write2_b32 v144, v40, v36 offset0:192 offset1:208
	v_add_u32_e32 v144, 0xc400, v0
	v_add_u32_e32 v145, 0xc800, v0
	v_add_u32_e32 v146, 0xcc00, v0
	ds_write2_b32 v0, v64, v60 offset1:16
	ds_write2_b32 v2, v65, v61 offset0:4 offset1:20
	ds_write2_b32 v3, v66, v62 offset0:8 offset1:24
	ds_write2_b32 v132, v67, v63 offset0:12 offset1:28
	ds_write2_b32 v133, v56, v52 offset0:64 offset1:80
	ds_write2_b32 v134, v57, v53 offset0:68 offset1:84
	ds_write2_b32 v135, v58, v54 offset0:72 offset1:88
	ds_write2_b32 v136, v59, v55 offset0:76 offset1:92
	ds_write2_b32 v141, v49, v45 offset0:132 offset1:148
	ds_write2_b32 v142, v50, v46 offset0:136 offset1:152
	ds_write2_b32 v143, v51, v47 offset0:140 offset1:156
	ds_write2_b32 v144, v41, v37 offset0:196 offset1:212
	ds_write2_b32 v145, v42, v38 offset0:200 offset1:216
	ds_write2_b32 v146, v43, v39 offset0:204 offset1:220
	ds_write2_b32 v0, v32, v28 offset0:128 offset1:144
	ds_write2_b32 v2, v33, v29 offset0:132 offset1:148
	ds_write2_b32 v3, v34, v30 offset0:136 offset1:152
	ds_write2_b32 v132, v35, v31 offset0:140 offset1:156
	ds_write2_b32 v133, v24, v20 offset0:192 offset1:208
	ds_write2_b32 v134, v25, v21 offset0:196 offset1:212
	ds_write2_b32 v135, v26, v22 offset0:200 offset1:216
	ds_write2_b32 v136, v27, v23 offset0:204 offset1:220
	ds_write2_b32 v141, v16, v12 offset1:16
	ds_write2_b32 v142, v17, v13 offset0:4 offset1:20
	ds_write2_b32 v143, v18, v14 offset0:8 offset1:24
	v_add_u32_e32 v2, 0x9000, v0
	v_add_u32_e32 v0, 0xd000, v0
	ds_write2_b32 v2, v19, v15 offset0:12 offset1:28
	ds_write2_b32 v144, v8, v4 offset0:64 offset1:80
	ds_write2_b32 v145, v9, v5 offset0:68 offset1:84
	ds_write2_b32 v146, v10, v6 offset0:72 offset1:88
	ds_write2_b32 v0, v11, v7 offset0:76 offset1:92
	v_mov_b32_e32 v0, v139
	s_waitcnt lgkmcnt(0)
	s_barrier
	s_addc_u32 s5, 0, s5
	v_ashrrev_i32_e32 v132, 5, v0
	v_ashrrev_i32_e32 v133, 31, v132
	v_lshlrev_b64 v[2:3], 12, v[132:133]
	v_and_b32_e32 v133, 31, v0
	v_lshl_add_u64 v[2:3], s[4:5], 0, v[2:3]
	v_lshlrev_b32_e32 v0, 3, v133
	v_lshl_add_u64 v[2:3], v[2:3], 0, v[0:1]
	v_mul_lo_u32 v0, v132, s81
	v_lshlrev_b32_e32 v132, 4, v133
	v_lshl_add_u64 v[2:3], s[66:67], 0, v[2:3]
	v_add3_u32 v0, v0, v132, 16
	s_mov_b64 s[4:5], 0
	ds_read_b128 v[232:235], v0
	ds_read_b128 v[236:239], v0 offset:512
.LBB0_507:
	v_add_u32_e32 v0, 0x4100, v0
	s_waitcnt lgkmcnt(0)
	v_cvt_pk_bf16_f32 v132, v232, v233
	v_cvt_pk_bf16_f32 v133, v234, v235
	v_cvt_pk_bf16_f32 v134, v236, v237
	v_lshl_add_u64 v[142:143], v[2:3], 0, s[4:5]
	s_add_u32 s4, s4, 0x10000
	v_add_co_u32_e32 v142, vcc, s2, v142
	s_addc_u32 s5, s5, 0
	s_nop 0
	v_addc_co_u32_e32 v143, vcc, 0, v143, vcc
	s_cmp_lg_u32 s4, 0x80000
	v_cvt_pk_bf16_f32 v135, v238, v239
	ds_read_b128 v[232:235], v0
	ds_read_b128 v[236:239], v0 offset:512
	global_store_dwordx2 v[142:143], v[132:133], off
	global_store_dwordx2 v[142:143], v[134:135], off offset:256
	s_cbranch_scc1 .LBB0_507
	s_add_i32 s1, s0, 1
	s_cmp_gt_i32 s0, 1
	s_mov_b32 s0, s1
	s_waitcnt lgkmcnt(0)
	s_barrier
	s_cbranch_scc0 .LBB0_496
	s_add_i32 s27, s27, 1
	s_mov_b64 s[0:1], 0
	s_branch .LBB0_489

; __device__ __forceinline__ int ltid() { int t = threadIdx.x; asm volatile("" : "+v"(t)); return t; }
; template <int AI>
; __device__ __forceinline__ void dump_half(const f32x4 (&acc)[2][2][4][2], float* stage) {
;   const int wid = ltid() >> 6, lane = ltid() & 63, wr = wid >> 2, wc = wid & 3, fr = lane & 15, fq = lane >> 4;
; #pragma unroll
;   for (int bj = 0; bj < 2; ++bj)
; #pragma unroll
;     for (int m = 0; m < 4; ++m)
; #pragma unroll
;       for (int n = 0; n < 2; ++n) {
;         const int r0 = wr * 64 + m * 16 + fq * 4, c = bj * 128 + wc * 32 + n * 16 + fr;
; #pragma unroll
;         for (int j = 0; j < 4; ++j) stage[(r0 + j) * SP + c] = acc[AI][bj][m][n][j];
;       }
; }
; __device__ __forceinline__ void emit_rm(const float* stage, u16* dst, long ld, const float* rs) {
;   const int tid = ltid(), c4 = (tid & 31) * 4, rr = tid >> 5;
; #pragma unroll 1
;   for (int ps = 0; ps < 8; ++ps) {
;     const int r = ps * 16 + rr;
;     const float* s = stage + r * SP + c4;
;     const float4 a = *(const float4*)s, b = *(const float4*)(s + 128);
;     const float f = rs ? rs[r] : 1.f;
;     uint2 o0, o1;
;     o0.x = pack2(a.x * f, a.y * f); o0.y = pack2(a.z * f, a.w * f);
;     o1.x = pack2(b.x * f, b.y * f); o1.y = pack2(b.z * f, b.w * f);
;     *(uint2*)(dst + (long)r * ld + c4) = o0;
;     *(uint2*)(dst + (long)r * ld + 128 + c4) = o1;
;   }
; }
; template <int KIND>
; __device__ __forceinline__ void tile_emit(const Ctx& p, int t, int hd, int s, int half, const float* stage) {
;     ...
;   } else if (KIND == G_G) {
;     int tb = t >> 6, tv = (t & 63) >> 3, tj = t & 7;
;     emit_rm(stage, (u16*)(ws + OFF_GTH) + (((long)tb * 3 + s) * 2048 + tv * 256 + hr) * 2048 + tj * 256, 2048, nullptr);
.LBB0_552:
	s_or_b64 exec, exec, s[4:5]
	v_mov_b32_e32 v0, v139
	v_mov_b32_e32 v2, v139
	s_barrier
	s_ashr_i32 s1, s27, 6
	v_lshrrev_b32_e32 v132, 2, v0
	v_and_b32_e32 v3, 15, v2
	v_and_b32_e32 v132, 0xfffffc0, v132
	v_lshrrev_b32_e32 v2, 2, v2
	v_lshlrev_b32_e32 v0, 1, v0
	v_and_or_b32 v2, v2, 12, v132
	v_and_b32_e32 v0, 0x180, v0
	v_add_u32_e32 v0, 16, v0
	v_lshlrev_b32_e32 v3, 2, v3
	v_mul_lo_u32 v2, v2, s81
	v_add3_u32 v0, v0, v3, v2
	v_add_u32_e32 v141, 0x8000, v0
	v_add_u32_e32 v144, 0xc000, v0
	v_add_u32_e32 v2, 0x400, v0
	v_add_u32_e32 v3, 0x800, v0
	v_add_u32_e32 v132, 0xc00, v0
	v_add_u32_e32 v133, 0x4000, v0
	v_add_u32_e32 v134, 0x4400, v0
	v_add_u32_e32 v135, 0x4800, v0
	v_add_u32_e32 v136, 0x4c00, v0
	ds_write2_b32 v141, v112, v108 offset0:128 offset1:144
	v_add_u32_e32 v141, 0x8400, v0
	v_add_u32_e32 v142, 0x8800, v0
	v_add_u32_e32 v143, 0x8c00, v0
	ds_write2_b32 v144, v104, v100 offset0:192 offset1:208
	v_add_u32_e32 v144, 0xc400, v0
	v_add_u32_e32 v145, 0xc800, v0
	v_add_u32_e32 v146, 0xcc00, v0
	s_mul_i32 s1, s1, 3
	ds_write2_b32 v0, v128, v124 offset1:16
	ds_write2_b32 v2, v129, v125 offset0:4 offset1:20
	ds_write2_b32 v3, v130, v126 offset0:8 offset1:24
	ds_write2_b32 v132, v131, v127 offset0:12 offset1:28
	ds_write2_b32 v133, v120, v116 offset0:64 offset1:80
	ds_write2_b32 v134, v121, v117 offset0:68 offset1:84
	ds_write2_b32 v135, v122, v118 offset0:72 offset1:88
	ds_write2_b32 v136, v123, v119 offset0:76 offset1:92
	ds_write2_b32 v141, v113, v109 offset0:132 offset1:148
	ds_write2_b32 v142, v114, v110 offset0:136 offset1:152
	ds_write2_b32 v143, v115, v111 offset0:140 offset1:156
	ds_write2_b32 v144, v105, v101 offset0:196 offset1:212
	ds_write2_b32 v145, v106, v102 offset0:200 offset1:216
	ds_write2_b32 v146, v107, v103 offset0:204 offset1:220
	ds_write2_b32 v0, v96, v92 offset0:128 offset1:144
	ds_write2_b32 v2, v97, v93 offset0:132 offset1:148
	ds_write2_b32 v3, v98, v94 offset0:136 offset1:152
	ds_write2_b32 v132, v99, v95 offset0:140 offset1:156
	ds_write2_b32 v133, v88, v84 offset0:192 offset1:208
	ds_write2_b32 v134, v89, v85 offset0:196 offset1:212
	ds_write2_b32 v135, v90, v86 offset0:200 offset1:216
	ds_write2_b32 v136, v91, v87 offset0:204 offset1:220
	ds_write2_b32 v141, v80, v76 offset1:16
	ds_write2_b32 v142, v81, v77 offset0:4 offset1:20
	ds_write2_b32 v143, v82, v78 offset0:8 offset1:24
	v_add_u32_e32 v2, 0x9000, v0
	v_add_u32_e32 v0, 0xd000, v0
	s_ashr_i32 s5, s1, 31
	s_ashr_i32 s6, s0, 31
	ds_write2_b32 v2, v83, v79 offset0:12 offset1:28
	ds_write2_b32 v144, v72, v68 offset0:64 offset1:80
	ds_write2_b32 v145, v73, v69 offset0:68 offset1:84
	ds_write2_b32 v146, v74, v70 offset0:72 offset1:88
	ds_write2_b32 v0, v75, v71 offset0:76 offset1:92
	s_add_u32 s4, s1, s0
	v_mov_b32_e32 v0, v139
	s_waitcnt lgkmcnt(0)
	s_barrier
	s_addc_u32 s5, s5, s6
	s_lshl_b32 s1, s27, 17
	s_and_b32 s1, s1, 0x700000
	v_ashrrev_i32_e32 v132, 5, v0
	s_lshl_b64 s[4:5], s[4:5], 23
	v_ashrrev_i32_e32 v133, 31, v132
	s_or_b32 s4, s4, s1
	v_lshlrev_b64 v[2:3], 12, v[132:133]
	s_lshl_b32 s1, s27, 9
	v_and_b32_e32 v0, 31, v0
	v_lshl_add_u64 v[2:3], s[4:5], 0, v[2:3]
	s_and_b32 s1, s1, 0xe00
	v_lshlrev_b32_e32 v133, 3, v0
	v_or3_b32 v2, v2, s1, v133
	v_mul_lo_u32 v132, v132, s81
	v_lshlrev_b32_e32 v0, 4, v0
	v_lshl_add_u64 v[2:3], s[66:67], 0, v[2:3]
	v_add3_u32 v0, v132, v0, 16
	s_mov_b64 s[6:7], 0
	ds_read_b128 v[232:235], v0
	ds_read_b128 v[236:239], v0 offset:512

; __device__ __forceinline__ int ltid() { int t = threadIdx.x; asm volatile("" : "+v"(t)); return t; }
; __device__ __forceinline__ void emit_rm(const float* stage, u16* dst, long ld, const float* rs) {
;   const int tid = ltid(), c4 = (tid & 31) * 4, rr = tid >> 5;
; #pragma unroll 1
;   for (int ps = 0; ps < 8; ++ps) {
;     const int r = ps * 16 + rr;
;     const float* s = stage + r * SP + c4;
;     const float4 a = *(const float4*)s, b = *(const float4*)(s + 128);
;     const float f = rs ? rs[r] : 1.f;
;     uint2 o0, o1;
;     o0.x = pack2(a.x * f, a.y * f); o0.y = pack2(a.z * f, a.w * f);
;     o1.x = pack2(b.x * f, b.y * f); o1.y = pack2(b.z * f, b.w * f);
;     *(uint2*)(dst + (long)r * ld + c4) = o0;
;     *(uint2*)(dst + (long)r * ld + 128 + c4) = o1;
;   }
; }
; template <int KIND>
; __device__ __forceinline__ void tile_emit(const Ctx& p, int t, int hd, int s, int half, const float* stage) {
;     ...
;   } else if (KIND == G_G) {
;     int tb = t >> 6, tv = (t & 63) >> 3, tj = t & 7;
;     emit_rm(stage, (u16*)(ws + OFF_GTH) + (((long)tb * 3 + s) * 2048 + tv * 256 + hr) * 2048 + tj * 256, 2048, nullptr);
.LBB0_555:
	v_add_u32_e32 v0, 0x4100, v0
	s_waitcnt lgkmcnt(0)
	v_cvt_pk_bf16_f32 v132, v232, v233
	v_cvt_pk_bf16_f32 v133, v234, v235
	v_cvt_pk_bf16_f32 v134, v236, v237
	v_lshl_add_u64 v[142:143], v[2:3], 0, s[4:5]
	s_add_u32 s4, s4, 0x10000
	v_add_co_u32_e32 v142, vcc, s2, v142
	s_addc_u32 s5, s5, 0
	s_nop 0
	v_addc_co_u32_e32 v143, vcc, 0, v143, vcc
	s_cmp_lg_u32 s4, 0x80000
	v_cvt_pk_bf16_f32 v135, v238, v239
	ds_read_b128 v[232:235], v0
	ds_read_b128 v[236:239], v0 offset:512
	global_store_dwordx2 v[142:143], v[132:133], off
	global_store_dwordx2 v[142:143], v[134:135], off offset:256
	s_cbranch_scc1 .LBB0_555
	s_add_i32 s1, s0, 1
	s_cmp_lt_i32 s0, 2
	s_mov_b32 s0, s1
	s_waitcnt lgkmcnt(0)
	s_barrier
	s_cbranch_scc1 .LBB0_544
